# v33 + code placement: each GEMM K-loop head aligned to 64 bytes
# speedup vs baseline: 1.0013x; 1.0013x over previous
; #define PG8_STAGE(bufoff, gbase, voff) do { _Pragma("unroll") for (int _i = 0; _i < 2; ++_i) \
;         __builtin_amdgcn_global_load_lds((const unsigned*)((const char*)(gbase) + (voff)[_i]), (PG8_LAS unsigned*)(lds + (bufoff) + ldsw + _i * 8192), 16, 0, 0); } while (0)
; #define PG8_LDA(dst, b, h) do { _Pragma("unroll") for (int m = 0; m < 4; ++m) _Pragma("unroll") for (int k = 0; k < 2; ++k) dst[m][k] = *(const PG8_LAS bf16x8*)(lds + PG8_SA(b, h) + aoff + m * 2048 + k * 1024); } while (0)
; template <class Epi, class Sched, bool ALIGN_EPI = false, bool SP2 = false>
; __device__ __forceinline__ void gemm_phase(PG8_LAS unsigned char* lds, const Gemm g, const Sched& S, const Epi& E) {
;     ...
;         const bool has_next = S.next(ui + 1, nxt);
;         const char* nA = has_next ? (const char*)g.A + (size_t)nxt.pm * tstepA : cA; const char* nB = has_next ? (const char*)g.Bt + (size_t)nxt.pn * tstep : cB;
;         for (int t = 0; t < nt; t += 2) {
;             const bool last = (t == nt - 2);
;             const char* a1 = cA + (size_t)(t + 1) * kstepA;
;             const char* a2 = last ? nA : cA + (size_t)(t + 2) * kstepA; const char* b2 = last ? nB : cB + (size_t)(t + 2) * kstep;
;             const char* a3 = a2 + kstepA; const char* b3 = b2 + kstep;
;             if (last && has_next) S.a_ready(nxt);
;             if constexpr (SP2) {
;             PG8_LDB(B0, 0, 0); PG8_LDB(B1, 0, 1); PG8_SCHED; PG8_LDA(At, 0, 0); PG8_STAGE(PG8_SA(1, 1), a1 + hstepA, voffA);
;             PG8_WAIT_V(8); PG8_WAIT_L(0); PG8_BAR; PG8_MMA(0, 0, At, B0); PG8_MMA(0, 1, At, B1); PG8_BAR; PG8_SCHED;
;             PG8_LDA(At, 0, 1); PG8_STAGE(PG8_SB(0, 0), b2, voffB); PG8_STAGE(PG8_SB(0, 1), b2 + hstep, voffB); PG8_STAGE(PG8_SA(0, 0), a2, voffA);
;             PG8_WAIT_V(8); PG8_WAIT_L(0); PG8_BAR; PG8_MMA(1, 0, At, B0); PG8_MMA(1, 1, At, B1); PG8_BAR; PG8_SCHED;
;             PG8_LDB(B0, 1, 0); PG8_LDB(B1, 1, 1); PG8_SCHED; PG8_LDA(At, 1, 0); PG8_STAGE(PG8_SA(0, 1), a2 + hstepA, voffA);
;             PG8_WAIT_V(8); PG8_WAIT_L(0); PG8_BAR; PG8_MMA(0, 0, At, B0); PG8_MMA(0, 1, At, B1); PG8_BAR; PG8_SCHED;
;             PG8_LDA(At, 1, 1); PG8_STAGE(PG8_SB(1, 0), b3, voffB); PG8_STAGE(PG8_SB(1, 1), b3 + hstep, voffB); PG8_STAGE(PG8_SA(1, 0), a3, voffA);
;             PG8_WAIT_V(8); PG8_WAIT_L(0); PG8_BAR; PG8_MMA(1, 0, At, B0); PG8_MMA(1, 1, At, B1); PG8_BAR; PG8_SCHED;
.LBB0_195:
	s_ashr_i32 s27, s26, 31
	s_lshl_b64 s[38:39], s[26:27], 19
	s_add_u32 s38, s20, s38
	s_addc_u32 s39, s21, s39
	s_and_b64 s[40:41], s[36:37], exec
	s_cselect_b32 s27, s39, s45
	s_cselect_b32 s54, s38, s44
	s_ashr_i32 s25, s24, 31
	s_lshl_b64 s[40:41], s[24:25], 19
	s_add_u32 s40, s2, s40
	s_addc_u32 s41, s3, s41
	s_and_b64 s[46:47], s[36:37], exec
	s_cselect_b32 s25, s41, s43
	s_cselect_b32 s55, s40, s42
	s_add_u32 s56, s42, 0x100
	s_addc_u32 s57, s43, 0
	s_add_u32 s42, s44, 0x40080
	s_addc_u32 s43, s45, 0
	s_mov_b32 s58, -2
	s_add_u32 s44, s42, 0xfffc0080
	s_addc_u32 s45, s43, -1
	s_add_i32 s59, 0, 0x10000
	s_cmp_eq_u32 s58, 12
	s_cselect_b32 s47, s27, s45
	s_cselect_b32 s46, s54, s44
	s_cselect_b32 s45, s25, s57
	s_cselect_b32 s44, s55, s56
	s_add_i32 s62, 0, 0x14000
	s_add_i32 m0, s7, 0xc000
	v_lshl_add_u64 v[166:167], s[42:43], 0, v[136:137]
	global_load_lds_dwordx4 v[166:167], off
	v_lshl_add_u64 v[166:167], s[42:43], 0, v[134:135]
	s_add_i32 m0, s7, 0xe000
	s_nop 0
	global_load_lds_dwordx4 v[166:167], off
	s_waitcnt vmcnt(8)
	s_waitcnt lgkmcnt(0)
	s_barrier
	s_setprio 1
	v_mfma_f32_16x16x32_bf16 v[124:127], v[138:141], v[192:195], 0
	v_mfma_f32_16x16x32_bf16 v[120:123], v[150:153], v[192:195], 0
	v_mfma_f32_16x16x32_bf16 v[116:119], v[138:141], v[200:203], 0
	v_mfma_f32_16x16x32_bf16 v[108:111], v[150:153], v[200:203], 0
	v_mfma_f32_16x16x32_bf16 v[100:103], v[138:141], v[208:211], 0
	v_mfma_f32_16x16x32_bf16 v[92:95], v[150:153], v[208:211], 0
	v_mfma_f32_16x16x32_bf16 v[84:87], v[138:141], v[216:219], 0
	v_mfma_f32_16x16x32_bf16 v[76:79], v[150:153], v[216:219], 0
	v_mfma_f32_16x16x32_bf16 v[124:127], v[146:149], v[196:199], v[124:127]
	v_mfma_f32_16x16x32_bf16 v[120:123], v[154:157], v[196:199], v[120:123]
	v_mfma_f32_16x16x32_bf16 v[116:119], v[146:149], v[204:207], v[116:119]
	v_mfma_f32_16x16x32_bf16 v[108:111], v[154:157], v[204:207], v[108:111]
	v_mfma_f32_16x16x32_bf16 v[100:103], v[146:149], v[212:215], v[100:103]
	v_mfma_f32_16x16x32_bf16 v[92:95], v[154:157], v[212:215], v[92:95]
	v_mfma_f32_16x16x32_bf16 v[84:87], v[146:149], v[220:223], v[84:87]
	v_mfma_f32_16x16x32_bf16 v[76:79], v[154:157], v[220:223], v[76:79]
	s_setprio 0
	s_setprio 1
	v_mfma_f32_16x16x32_bf16 v[112:115], v[158:161], v[192:195], 0
	v_mfma_f32_16x16x32_bf16 v[104:107], v[170:173], v[192:195], 0
	v_mfma_f32_16x16x32_bf16 v[96:99], v[158:161], v[200:203], 0
	v_mfma_f32_16x16x32_bf16 v[88:91], v[170:173], v[200:203], 0
	v_mfma_f32_16x16x32_bf16 v[80:83], v[158:161], v[208:211], 0
	v_mfma_f32_16x16x32_bf16 v[72:75], v[170:173], v[208:211], 0
	v_mfma_f32_16x16x32_bf16 v[68:71], v[158:161], v[216:219], 0
	v_mfma_f32_16x16x32_bf16 v[64:67], v[170:173], v[216:219], 0
	v_mfma_f32_16x16x32_bf16 v[112:115], v[162:165], v[196:199], v[112:115]
	v_mfma_f32_16x16x32_bf16 v[104:107], v[188:191], v[196:199], v[104:107]
	v_mfma_f32_16x16x32_bf16 v[96:99], v[162:165], v[204:207], v[96:99]
	v_mfma_f32_16x16x32_bf16 v[88:91], v[188:191], v[204:207], v[88:91]
	v_mfma_f32_16x16x32_bf16 v[80:83], v[162:165], v[212:215], v[80:83]
	s_add_i32 s59, s59, s6
	v_mfma_f32_16x16x32_bf16 v[72:75], v[188:191], v[212:215], v[72:75]
	v_lshl_add_u64 v[166:167], s[44:45], 0, v[168:169]
	v_mfma_f32_16x16x32_bf16 v[68:71], v[162:165], v[220:223], v[68:71]
	s_mov_b32 m0, s59
	v_mfma_f32_16x16x32_bf16 v[64:67], v[188:191], v[220:223], v[64:67]
	s_setprio 0
	s_barrier
	ds_read_b128 v[192:195], v145 offset:16384
	ds_read_b128 v[196:199], v145 offset:17408
	ds_read_b128 v[200:203], v145 offset:18432
	ds_read_b128 v[204:207], v145 offset:19456
	ds_read_b128 v[208:211], v145 offset:20480
	ds_read_b128 v[212:215], v145 offset:21504
	ds_read_b128 v[216:219], v145 offset:22528
	ds_read_b128 v[220:223], v145 offset:23552
	global_load_lds_dwordx4 v[166:167], off
	s_add_i32 m0, s59, 0x2000
	s_add_u32 s60, s44, 0x40000
	v_lshl_add_u64 v[178:179], s[44:45], 0, v[128:129]
	s_addc_u32 s61, s45, 0
	s_add_i32 s59, s62, s6
	global_load_lds_dwordx4 v[178:179], off
	v_lshl_add_u64 v[224:225], s[60:61], 0, v[168:169]
	s_mov_b32 m0, s59
	v_lshl_add_u64 v[234:235], s[46:47], 0, v[130:131]
	global_load_lds_dwordx4 v[224:225], off
	v_lshl_add_u64 v[224:225], s[60:61], 0, v[128:129]
	s_add_i32 m0, s59, 0x2000
	s_nop 0
	global_load_lds_dwordx4 v[224:225], off
	v_lshl_add_u64 v[224:225], s[46:47], 0, v[132:133]
	s_mov_b32 m0, s7
	s_nop 0
	global_load_lds_dwordx4 v[224:225], off
	s_mov_b32 m0, s34
	s_nop 0
	global_load_lds_dwordx4 v[234:235], off
	s_waitcnt vmcnt(8)
	s_waitcnt lgkmcnt(0)
	s_barrier
; #define PG8_STAGE(bufoff, gbase, voff) do { _Pragma("unroll") for (int _i = 0; _i < 2; ++_i) \
;         __builtin_amdgcn_global_load_lds((const unsigned*)((const char*)(gbase) + (voff)[_i]), (PG8_LAS unsigned*)(lds + (bufoff) + ldsw + _i * 8192), 16, 0, 0); } while (0)
; #define PG8_LDA(dst, b, h) do { _Pragma("unroll") for (int m = 0; m < 4; ++m) _Pragma("unroll") for (int k = 0; k < 2; ++k) dst[m][k] = *(const PG8_LAS bf16x8*)(lds + PG8_SA(b, h) + aoff + m * 2048 + k * 1024); } while (0)
; #define PG8_LDB(dst, b, h) do { _Pragma("unroll") for (int n = 0; n < 2; ++n) _Pragma("unroll") for (int k = 0; k < 2; ++k) dst[n][k] = *(const PG8_LAS bf16x8*)(lds + PG8_SB(b, h) + boff + n * 2048 + k * 1024); } while (0)
; #define PG8_MMA(ai, bj, At, Bt) do { __builtin_amdgcn_s_setprio(1); _Pragma("unroll") for (int m = 0; m < 4; ++m) _Pragma("unroll") for (int n = 0; n < 2; ++n) _Pragma("unroll") for (int k = 0; k < 2; ++k) \
;         acc[ai][bj][m][n] = __builtin_amdgcn_mfma_f32_16x16x32_bf16(Bt[n][k], At[m][k], acc[ai][bj][m][n], 0, 0, 0); __builtin_amdgcn_s_setprio(0); } while (0)
; #define PG8_WAIT_V(n) asm volatile("s_waitcnt vmcnt(" #n ")" ::: "memory")
; #define PG8_WAIT_L(n) asm volatile("s_waitcnt lgkmcnt(" #n ")" ::: "memory")
; #define PG8_BAR __builtin_amdgcn_s_barrier()
; #define PG8_SCHED __builtin_amdgcn_sched_barrier(0)
; template <class Epi, class Sched, bool ALIGN_EPI = false, bool SP2 = false>
; __device__ __forceinline__ void gemm_phase(PG8_LAS unsigned char* lds, const Gemm g, const Sched& S, const Epi& E) {
;     ...
;             PG8_LDB(B0, 0, 0); PG8_LDB(B1, 0, 1); PG8_SCHED; PG8_LDA(At, 0, 0); PG8_STAGE(PG8_SA(1, 1), a1 + hstepA, voffA);
;             PG8_WAIT_V(8); PG8_WAIT_L(0); PG8_BAR; PG8_MMA(0, 0, At, B0); PG8_MMA(0, 1, At, B1); PG8_BAR; PG8_SCHED;
;             PG8_LDA(At, 0, 1); PG8_STAGE(PG8_SB(0, 0), b2, voffB); PG8_STAGE(PG8_SB(0, 1), b2 + hstep, voffB); PG8_STAGE(PG8_SA(0, 0), a2, voffA);
;             PG8_WAIT_V(8); PG8_WAIT_L(0); PG8_BAR; PG8_MMA(1, 0, At, B0); PG8_MMA(1, 1, At, B1); PG8_BAR; PG8_SCHED;
;             PG8_LDB(B0, 1, 0); PG8_LDB(B1, 1, 1); PG8_SCHED; PG8_LDA(At, 1, 0); PG8_STAGE(PG8_SA(0, 1), a2 + hstepA, voffA);
;             PG8_WAIT_V(8); PG8_WAIT_L(0); PG8_BAR; PG8_MMA(0, 0, At, B0); PG8_MMA(0, 1, At, B1); PG8_BAR; PG8_SCHED;
	s_setprio 1
	v_mfma_f32_16x16x32_bf16 v[60:63], v[138:141], v[192:195], 0
	v_mfma_f32_16x16x32_bf16 v[56:59], v[150:153], v[192:195], 0
	v_mfma_f32_16x16x32_bf16 v[52:55], v[138:141], v[200:203], 0
	v_mfma_f32_16x16x32_bf16 v[44:47], v[150:153], v[200:203], 0
	v_mfma_f32_16x16x32_bf16 v[36:39], v[138:141], v[208:211], 0
	v_mfma_f32_16x16x32_bf16 v[28:31], v[150:153], v[208:211], 0
	v_mfma_f32_16x16x32_bf16 v[20:23], v[138:141], v[216:219], 0
	v_mfma_f32_16x16x32_bf16 v[12:15], v[150:153], v[216:219], 0
	v_mfma_f32_16x16x32_bf16 v[60:63], v[146:149], v[196:199], v[60:63]
	v_mfma_f32_16x16x32_bf16 v[56:59], v[154:157], v[196:199], v[56:59]
	v_mfma_f32_16x16x32_bf16 v[52:55], v[146:149], v[204:207], v[52:55]
	v_mfma_f32_16x16x32_bf16 v[44:47], v[154:157], v[204:207], v[44:47]
	v_mfma_f32_16x16x32_bf16 v[36:39], v[146:149], v[212:215], v[36:39]
	v_mfma_f32_16x16x32_bf16 v[28:31], v[154:157], v[212:215], v[28:31]
	v_mfma_f32_16x16x32_bf16 v[20:23], v[146:149], v[220:223], v[20:23]
	v_mfma_f32_16x16x32_bf16 v[12:15], v[154:157], v[220:223], v[12:15]
	s_setprio 0
	s_setprio 1
	v_mfma_f32_16x16x32_bf16 v[48:51], v[158:161], v[192:195], 0
	v_mfma_f32_16x16x32_bf16 v[40:43], v[170:173], v[192:195], 0
	v_mfma_f32_16x16x32_bf16 v[32:35], v[158:161], v[200:203], 0
	v_mfma_f32_16x16x32_bf16 v[24:27], v[170:173], v[200:203], 0
	v_mfma_f32_16x16x32_bf16 v[16:19], v[158:161], v[208:211], 0
	v_mfma_f32_16x16x32_bf16 v[8:11], v[170:173], v[208:211], 0
	v_mfma_f32_16x16x32_bf16 v[4:7], v[158:161], v[216:219], 0
	v_mfma_f32_16x16x32_bf16 v[0:3], v[170:173], v[216:219], 0
	v_mfma_f32_16x16x32_bf16 v[48:51], v[162:165], v[196:199], v[48:51]
	v_mfma_f32_16x16x32_bf16 v[40:43], v[188:191], v[196:199], v[40:43]
	v_mfma_f32_16x16x32_bf16 v[32:35], v[162:165], v[204:207], v[32:35]
	v_mfma_f32_16x16x32_bf16 v[24:27], v[188:191], v[204:207], v[24:27]
	s_add_i32 s59, 0, 0x18000
	v_mfma_f32_16x16x32_bf16 v[16:19], v[162:165], v[212:215], v[16:19]
	s_add_i32 s60, 0, 0x1c000
	v_mfma_f32_16x16x32_bf16 v[8:11], v[188:191], v[212:215], v[8:11]
	v_add_u32_e32 v240, s59, v143
	v_mfma_f32_16x16x32_bf16 v[4:7], v[162:165], v[220:223], v[4:7]
	v_add_u32_e32 v241, s60, v143
	v_mfma_f32_16x16x32_bf16 v[0:3], v[188:191], v[220:223], v[0:3]
	s_setprio 0
	s_barrier
	ds_read_b128 v[138:141], v240
	ds_read_b128 v[146:149], v240 offset:1024
	ds_read_b128 v[150:153], v240 offset:2048
	ds_read_b128 v[154:157], v240 offset:3072
	ds_read_b128 v[158:161], v241
	ds_read_b128 v[162:165], v241 offset:1024
	ds_read_b128 v[170:173], v241 offset:2048
	ds_read_b128 v[188:191], v241 offset:3072
	ds_read_b128 v[192:195], v145 offset:32768
	ds_read_b128 v[196:199], v145 offset:33792
	ds_read_b128 v[200:203], v145 offset:34816
	ds_read_b128 v[204:207], v145 offset:35840
	ds_read_b128 v[208:211], v145 offset:36864
	ds_read_b128 v[212:215], v145 offset:37888
	ds_read_b128 v[216:219], v145 offset:38912
	ds_read_b128 v[220:223], v145 offset:39936
	s_add_u32 s46, s46, 0x40000
	s_addc_u32 s47, s47, 0
	s_mov_b32 m0, s35
	v_lshl_add_u64 v[236:237], s[46:47], 0, v[132:133]
	global_load_lds_dwordx4 v[236:237], off
	v_lshl_add_u64 v[236:237], s[46:47], 0, v[130:131]
	s_mov_b32 m0, s48
	s_nop 0
	global_load_lds_dwordx4 v[236:237], off
	s_waitcnt vmcnt(8)
	s_waitcnt lgkmcnt(0)
	s_barrier
	s_setprio 1
	v_mfma_f32_16x16x32_bf16 v[124:127], v[138:141], v[192:195], v[124:127]
	v_mfma_f32_16x16x32_bf16 v[120:123], v[150:153], v[192:195], v[120:123]
	v_mfma_f32_16x16x32_bf16 v[116:119], v[138:141], v[200:203], v[116:119]
	v_mfma_f32_16x16x32_bf16 v[108:111], v[150:153], v[200:203], v[108:111]
	v_mfma_f32_16x16x32_bf16 v[100:103], v[138:141], v[208:211], v[100:103]
	v_mfma_f32_16x16x32_bf16 v[92:95], v[150:153], v[208:211], v[92:95]
	v_mfma_f32_16x16x32_bf16 v[84:87], v[138:141], v[216:219], v[84:87]
	v_mfma_f32_16x16x32_bf16 v[76:79], v[150:153], v[216:219], v[76:79]
	v_mfma_f32_16x16x32_bf16 v[124:127], v[146:149], v[196:199], v[124:127]
	v_mfma_f32_16x16x32_bf16 v[120:123], v[154:157], v[196:199], v[120:123]
	v_mfma_f32_16x16x32_bf16 v[116:119], v[146:149], v[204:207], v[116:119]
	v_mfma_f32_16x16x32_bf16 v[108:111], v[154:157], v[204:207], v[108:111]
	v_mfma_f32_16x16x32_bf16 v[100:103], v[146:149], v[212:215], v[100:103]
	v_mfma_f32_16x16x32_bf16 v[92:95], v[154:157], v[212:215], v[92:95]
	v_mfma_f32_16x16x32_bf16 v[84:87], v[146:149], v[220:223], v[84:87]
	v_mfma_f32_16x16x32_bf16 v[76:79], v[154:157], v[220:223], v[76:79]
	s_setprio 0
	s_setprio 1
	v_mfma_f32_16x16x32_bf16 v[112:115], v[158:161], v[192:195], v[112:115]
	v_mfma_f32_16x16x32_bf16 v[104:107], v[170:173], v[192:195], v[104:107]
	v_mfma_f32_16x16x32_bf16 v[96:99], v[158:161], v[200:203], v[96:99]
	v_mfma_f32_16x16x32_bf16 v[88:91], v[170:173], v[200:203], v[88:91]
	v_mfma_f32_16x16x32_bf16 v[80:83], v[158:161], v[208:211], v[80:83]
	v_mfma_f32_16x16x32_bf16 v[72:75], v[170:173], v[208:211], v[72:75]
	v_mfma_f32_16x16x32_bf16 v[68:71], v[158:161], v[216:219], v[68:71]
	v_mfma_f32_16x16x32_bf16 v[64:67], v[170:173], v[216:219], v[64:67]
	v_mfma_f32_16x16x32_bf16 v[112:115], v[162:165], v[196:199], v[112:115]
	v_mfma_f32_16x16x32_bf16 v[104:107], v[188:191], v[196:199], v[104:107]
	v_mfma_f32_16x16x32_bf16 v[96:99], v[162:165], v[204:207], v[96:99]
	v_mfma_f32_16x16x32_bf16 v[88:91], v[188:191], v[204:207], v[88:91]
	v_mfma_f32_16x16x32_bf16 v[80:83], v[162:165], v[212:215], v[80:83]
	s_add_i32 s46, s59, s6
	v_mfma_f32_16x16x32_bf16 v[72:75], v[188:191], v[212:215], v[72:75]
	v_lshl_add_u64 v[166:167], v[166:167], 0, s[30:31]
	v_mfma_f32_16x16x32_bf16 v[68:71], v[162:165], v[220:223], v[68:71]
	s_mov_b32 m0, s46
	v_mfma_f32_16x16x32_bf16 v[64:67], v[188:191], v[220:223], v[64:67]
	s_setprio 0
	s_barrier
; #define PG8_STAGE(bufoff, gbase, voff) do { _Pragma("unroll") for (int _i = 0; _i < 2; ++_i) \
;         __builtin_amdgcn_global_load_lds((const unsigned*)((const char*)(gbase) + (voff)[_i]), (PG8_LAS unsigned*)(lds + (bufoff) + ldsw + _i * 8192), 16, 0, 0); } while (0)
; #define PG8_LDA(dst, b, h) do { _Pragma("unroll") for (int m = 0; m < 4; ++m) _Pragma("unroll") for (int k = 0; k < 2; ++k) dst[m][k] = *(const PG8_LAS bf16x8*)(lds + PG8_SA(b, h) + aoff + m * 2048 + k * 1024); } while (0)
; #define PG8_LDB(dst, b, h) do { _Pragma("unroll") for (int n = 0; n < 2; ++n) _Pragma("unroll") for (int k = 0; k < 2; ++k) dst[n][k] = *(const PG8_LAS bf16x8*)(lds + PG8_SB(b, h) + boff + n * 2048 + k * 1024); } while (0)
; template <class Epi, class Sched, bool ALIGN_EPI = false, bool SP2 = false>
; __device__ __forceinline__ void gemm_phase(PG8_LAS unsigned char* lds, const Gemm g, const Sched& S, const Epi& E) {
;     ...
;         for (int t = 0; t < nt; t += 2) {
;             const bool last = (t == nt - 2);
;             const char* a1 = cA + (size_t)(t + 1) * kstepA;
;             const char* a2 = last ? nA : cA + (size_t)(t + 2) * kstepA; const char* b2 = last ? nB : cB + (size_t)(t + 2) * kstep;
;             const char* a3 = a2 + kstepA; const char* b3 = b2 + kstep;
;             if (last && has_next) S.a_ready(nxt);
;             if constexpr (SP2) {
;             PG8_LDB(B0, 0, 0); PG8_LDB(B1, 0, 1); PG8_SCHED; PG8_LDA(At, 0, 0); PG8_STAGE(PG8_SA(1, 1), a1 + hstepA, voffA);
;             PG8_WAIT_V(8); PG8_WAIT_L(0); PG8_BAR; PG8_MMA(0, 0, At, B0); PG8_MMA(0, 1, At, B1); PG8_BAR; PG8_SCHED;
;             PG8_LDA(At, 0, 1); PG8_STAGE(PG8_SB(0, 0), b2, voffB); PG8_STAGE(PG8_SB(0, 1), b2 + hstep, voffB); PG8_STAGE(PG8_SA(0, 0), a2, voffA);
;             PG8_WAIT_V(8); PG8_WAIT_L(0); PG8_BAR; PG8_MMA(1, 0, At, B0); PG8_MMA(1, 1, At, B1); PG8_BAR; PG8_SCHED;
;             PG8_LDB(B0, 1, 0); PG8_LDB(B1, 1, 1); PG8_SCHED; PG8_LDA(At, 1, 0); PG8_STAGE(PG8_SA(0, 1), a2 + hstepA, voffA);
;             PG8_WAIT_V(8); PG8_WAIT_L(0); PG8_BAR; PG8_MMA(0, 0, At, B0); PG8_MMA(0, 1, At, B1); PG8_BAR; PG8_SCHED;
;             PG8_LDA(At, 1, 1); PG8_STAGE(PG8_SB(1, 0), b3, voffB); PG8_STAGE(PG8_SB(1, 1), b3 + hstep, voffB); PG8_STAGE(PG8_SA(1, 0), a3, voffA);
;             PG8_WAIT_V(8); PG8_WAIT_L(0); PG8_BAR; PG8_MMA(1, 0, At, B0); PG8_MMA(1, 1, At, B1); PG8_BAR; PG8_SCHED;
	ds_read_b128 v[192:195], v145 offset:49152
	ds_read_b128 v[196:199], v145 offset:50176
	ds_read_b128 v[200:203], v145 offset:51200
	ds_read_b128 v[204:207], v145 offset:52224
	ds_read_b128 v[208:211], v145 offset:53248
	ds_read_b128 v[212:215], v145 offset:54272
	ds_read_b128 v[216:219], v145 offset:55296
	ds_read_b128 v[220:223], v145 offset:56320
	global_load_lds_dwordx4 v[166:167], off
	s_add_i32 m0, s46, 0x2000
	s_add_u32 s44, s44, 0x40080
	v_lshl_add_u64 v[166:167], v[178:179], 0, s[30:31]
	s_addc_u32 s45, s45, 0
	s_add_i32 s46, s60, s6
	global_load_lds_dwordx4 v[166:167], off
	v_lshl_add_u64 v[166:167], s[44:45], 0, v[168:169]
	s_mov_b32 m0, s46
	s_nop 0
	global_load_lds_dwordx4 v[166:167], off
	v_lshl_add_u64 v[166:167], s[44:45], 0, v[128:129]
	s_add_i32 m0, s46, 0x2000
	s_nop 0
	global_load_lds_dwordx4 v[166:167], off
	v_lshl_add_u64 v[166:167], v[224:225], 0, s[30:31]
	s_mov_b32 m0, s49
	s_nop 0
	global_load_lds_dwordx4 v[166:167], off
	v_lshl_add_u64 v[166:167], v[234:235], 0, s[30:31]
	s_mov_b32 m0, s50
	s_nop 0
	global_load_lds_dwordx4 v[166:167], off
	s_waitcnt vmcnt(8)
	s_waitcnt lgkmcnt(0)
	s_barrier
	s_setprio 1
	v_mfma_f32_16x16x32_bf16 v[60:63], v[138:141], v[192:195], v[60:63]
	v_mfma_f32_16x16x32_bf16 v[56:59], v[150:153], v[192:195], v[56:59]
	v_mfma_f32_16x16x32_bf16 v[52:55], v[138:141], v[200:203], v[52:55]
	v_mfma_f32_16x16x32_bf16 v[44:47], v[150:153], v[200:203], v[44:47]
	v_mfma_f32_16x16x32_bf16 v[36:39], v[138:141], v[208:211], v[36:39]
	v_mfma_f32_16x16x32_bf16 v[28:31], v[150:153], v[208:211], v[28:31]
	v_mfma_f32_16x16x32_bf16 v[20:23], v[138:141], v[216:219], v[20:23]
	v_mfma_f32_16x16x32_bf16 v[12:15], v[150:153], v[216:219], v[12:15]
	v_mfma_f32_16x16x32_bf16 v[60:63], v[146:149], v[196:199], v[60:63]
	v_mfma_f32_16x16x32_bf16 v[56:59], v[154:157], v[196:199], v[56:59]
	v_mfma_f32_16x16x32_bf16 v[52:55], v[146:149], v[204:207], v[52:55]
	v_mfma_f32_16x16x32_bf16 v[44:47], v[154:157], v[204:207], v[44:47]
	v_mfma_f32_16x16x32_bf16 v[36:39], v[146:149], v[212:215], v[36:39]
	v_mfma_f32_16x16x32_bf16 v[28:31], v[154:157], v[212:215], v[28:31]
	v_mfma_f32_16x16x32_bf16 v[20:23], v[146:149], v[220:223], v[20:23]
	v_mfma_f32_16x16x32_bf16 v[12:15], v[154:157], v[220:223], v[12:15]
	s_add_i32 s58, s58, 2
	s_setprio 0
	s_setprio 1
	v_mfma_f32_16x16x32_bf16 v[48:51], v[158:161], v[192:195], v[48:51]
	s_add_u32 s56, s56, 0x100
	v_mfma_f32_16x16x32_bf16 v[40:43], v[170:173], v[192:195], v[40:43]
	s_addc_u32 s57, s57, 0
	v_mfma_f32_16x16x32_bf16 v[32:35], v[158:161], v[200:203], v[32:35]
	s_add_u32 s42, s42, 0x100
	v_mfma_f32_16x16x32_bf16 v[24:27], v[170:173], v[200:203], v[24:27]
	s_addc_u32 s43, s43, 0
	v_mfma_f32_16x16x32_bf16 v[16:19], v[158:161], v[208:211], v[16:19]
	s_add_u32 s44, s42, 0xfffc0080
	v_mfma_f32_16x16x32_bf16 v[8:11], v[170:173], v[208:211], v[8:11]
	s_addc_u32 s45, s43, -1
	v_mfma_f32_16x16x32_bf16 v[4:7], v[158:161], v[216:219], v[4:7]
	s_add_i32 s59, 0, 0x10000
	v_mfma_f32_16x16x32_bf16 v[0:3], v[170:173], v[216:219], v[0:3]
	s_cmp_eq_u32 s58, 12
	v_mfma_f32_16x16x32_bf16 v[48:51], v[162:165], v[196:199], v[48:51]
	s_cselect_b32 s47, s27, s45
	v_mfma_f32_16x16x32_bf16 v[40:43], v[188:191], v[196:199], v[40:43]
	s_cselect_b32 s46, s54, s44
	v_mfma_f32_16x16x32_bf16 v[32:35], v[162:165], v[204:207], v[32:35]
	s_cselect_b32 s45, s25, s57
	v_mfma_f32_16x16x32_bf16 v[24:27], v[188:191], v[204:207], v[24:27]
	s_cselect_b32 s44, s55, s56
	v_mfma_f32_16x16x32_bf16 v[16:19], v[162:165], v[212:215], v[16:19]
	s_add_i32 s62, 0, 0x14000
	v_mfma_f32_16x16x32_bf16 v[8:11], v[188:191], v[212:215], v[8:11]
	v_add_u32_e32 v242, s59, v143
	v_mfma_f32_16x16x32_bf16 v[4:7], v[162:165], v[220:223], v[4:7]
	v_add_u32_e32 v166, s62, v143
	v_mfma_f32_16x16x32_bf16 v[0:3], v[188:191], v[220:223], v[0:3]
	s_setprio 0
	s_barrier
	.p2align	6

; #define PG8_STAGE(bufoff, gbase, voff) do { _Pragma("unroll") for (int _i = 0; _i < 2; ++_i) \
;         __builtin_amdgcn_global_load_lds((const unsigned*)((const char*)(gbase) + (voff)[_i]), (PG8_LAS unsigned*)(lds + (bufoff) + ldsw + _i * 8192), 16, 0, 0); } while (0)
; #define PG8_LDA(dst, b, h) do { _Pragma("unroll") for (int m = 0; m < 4; ++m) _Pragma("unroll") for (int k = 0; k < 2; ++k) dst[m][k] = *(const PG8_LAS bf16x8*)(lds + PG8_SA(b, h) + aoff + m * 2048 + k * 1024); } while (0)
; #define PG8_BAR __builtin_amdgcn_s_barrier()
; template <class Epi, class Sched, bool ALIGN_EPI = false, bool SP2 = false>
; __device__ __forceinline__ void gemm_phase(PG8_LAS unsigned char* lds, const Gemm g, const Sched& S, const Epi& E) {
;     ...
;         const char* nA = has_next ? (const char*)g.A + (size_t)nxt.pm * tstepA : cA; const char* nB = has_next ? (const char*)g.Bt + (size_t)nxt.pn * tstep : cB;
;         for (int t = 0; t < nt; t += 2) {
;             const bool last = (t == nt - 2);
;             const char* a1 = cA + (size_t)(t + 1) * kstepA;
;             const char* a2 = last ? nA : cA + (size_t)(t + 2) * kstepA; const char* b2 = last ? nB : cB + (size_t)(t + 2) * kstep;
;             const char* a3 = a2 + kstepA; const char* b3 = b2 + kstep;
;             if (last && has_next) S.a_ready(nxt);
;             if constexpr (SP2) {
;             PG8_LDB(B0, 0, 0); PG8_LDB(B1, 0, 1); PG8_SCHED; PG8_LDA(At, 0, 0); PG8_STAGE(PG8_SA(1, 1), a1 + hstepA, voffA);
;             PG8_WAIT_V(8); PG8_WAIT_L(0); PG8_BAR; PG8_MMA(0, 0, At, B0); PG8_MMA(0, 1, At, B1); PG8_BAR; PG8_SCHED;
;             PG8_LDA(At, 0, 1); PG8_STAGE(PG8_SB(0, 0), b2, voffB); PG8_STAGE(PG8_SB(0, 1), b2 + hstep, voffB); PG8_STAGE(PG8_SA(0, 0), a2, voffA);
;             PG8_WAIT_V(8); PG8_WAIT_L(0); PG8_BAR; PG8_MMA(1, 0, At, B0); PG8_MMA(1, 1, At, B1); PG8_BAR; PG8_SCHED;
;             PG8_LDB(B0, 1, 0); PG8_LDB(B1, 1, 1); PG8_SCHED; PG8_LDA(At, 1, 0); PG8_STAGE(PG8_SA(0, 1), a2 + hstepA, voffA);
;             PG8_WAIT_V(8); PG8_WAIT_L(0); PG8_BAR; PG8_MMA(0, 0, At, B0); PG8_MMA(0, 1, At, B1); PG8_BAR; PG8_SCHED;
;             PG8_LDA(At, 1, 1); PG8_STAGE(PG8_SB(1, 0), b3, voffB); PG8_STAGE(PG8_SB(1, 1), b3 + hstep, voffB); PG8_STAGE(PG8_SA(1, 0), a3, voffA);
;             PG8_WAIT_V(8); PG8_WAIT_L(0); PG8_BAR; PG8_MMA(1, 0, At, B0); PG8_MMA(1, 1, At, B1); PG8_BAR; PG8_SCHED;
.LBB0_433:
	s_ashr_i32 s41, s40, 31
	s_lshl_b64 s[42:43], s[40:41], 19
	s_add_u32 s42, s20, s42
	s_addc_u32 s43, s21, s43
	s_and_b64 s[44:45], s[36:37], exec
	s_cselect_b32 s41, s43, s39
	s_cselect_b32 s54, s42, s38
	s_ashr_i32 s27, s26, 31
	s_lshl_b64 s[44:45], s[26:27], 19
	s_add_u32 s44, s3, s44
	s_addc_u32 s45, s6, s45
	s_and_b64 s[46:47], s[36:37], exec
	s_cselect_b32 s27, s45, s5
	s_cselect_b32 s55, s44, s4
	s_add_u32 s56, s4, 0x100
	s_addc_u32 s57, s5, 0
	s_add_u32 s4, s38, 0x40080
	s_addc_u32 s5, s39, 0
	s_mov_b32 s58, -2
	s_add_u32 s38, s4, 0xfffc0080
	s_addc_u32 s39, s5, -1
	s_add_i32 s59, 0, 0x10000
	s_cmp_eq_u32 s58, 12
	s_cselect_b32 s47, s41, s39
	s_cselect_b32 s46, s54, s38
	s_cselect_b32 s39, s27, s57
	s_cselect_b32 s38, s55, s56
	s_add_i32 s62, 0, 0x14000
	s_add_i32 m0, s2, 0xc000
	v_lshl_add_u64 v[166:167], s[4:5], 0, v[136:137]
	global_load_lds_dwordx4 v[166:167], off
	v_lshl_add_u64 v[166:167], s[4:5], 0, v[134:135]
	s_add_i32 m0, s2, 0xe000
	s_nop 0
	global_load_lds_dwordx4 v[166:167], off
	s_waitcnt vmcnt(8)
	s_waitcnt lgkmcnt(0)
	s_barrier
	s_setprio 1
	v_mfma_f32_16x16x32_bf16 v[124:127], v[138:141], v[196:199], 0
	v_mfma_f32_16x16x32_bf16 v[120:123], v[150:153], v[196:199], 0
	v_mfma_f32_16x16x32_bf16 v[108:111], v[138:141], v[204:207], 0
	v_mfma_f32_16x16x32_bf16 v[104:107], v[150:153], v[204:207], 0
	v_mfma_f32_16x16x32_bf16 v[92:95], v[138:141], v[212:215], 0
	v_mfma_f32_16x16x32_bf16 v[88:91], v[150:153], v[212:215], 0
	v_mfma_f32_16x16x32_bf16 v[76:79], v[138:141], v[220:223], 0
	v_mfma_f32_16x16x32_bf16 v[72:75], v[150:153], v[220:223], 0
	v_mfma_f32_16x16x32_bf16 v[124:127], v[146:149], v[200:203], v[124:127]
	v_mfma_f32_16x16x32_bf16 v[120:123], v[154:157], v[200:203], v[120:123]
	v_mfma_f32_16x16x32_bf16 v[108:111], v[146:149], v[208:211], v[108:111]
	v_mfma_f32_16x16x32_bf16 v[104:107], v[154:157], v[208:211], v[104:107]
	v_mfma_f32_16x16x32_bf16 v[92:95], v[146:149], v[216:219], v[92:95]
	v_mfma_f32_16x16x32_bf16 v[88:91], v[154:157], v[216:219], v[88:91]
	v_mfma_f32_16x16x32_bf16 v[76:79], v[146:149], v[234:237], v[76:79]
	v_mfma_f32_16x16x32_bf16 v[72:75], v[154:157], v[234:237], v[72:75]
	s_setprio 0
	s_setprio 1
	v_mfma_f32_16x16x32_bf16 v[116:119], v[158:161], v[196:199], 0
	v_mfma_f32_16x16x32_bf16 v[112:115], v[188:191], v[196:199], 0
	v_mfma_f32_16x16x32_bf16 v[100:103], v[158:161], v[204:207], 0
	v_mfma_f32_16x16x32_bf16 v[96:99], v[188:191], v[204:207], 0
	v_mfma_f32_16x16x32_bf16 v[84:87], v[158:161], v[212:215], 0
	v_mfma_f32_16x16x32_bf16 v[80:83], v[188:191], v[212:215], 0
	v_mfma_f32_16x16x32_bf16 v[68:71], v[158:161], v[220:223], 0
	v_mfma_f32_16x16x32_bf16 v[64:67], v[188:191], v[220:223], 0
	v_mfma_f32_16x16x32_bf16 v[116:119], v[162:165], v[200:203], v[116:119]
	v_mfma_f32_16x16x32_bf16 v[112:115], v[192:195], v[200:203], v[112:115]
	v_mfma_f32_16x16x32_bf16 v[100:103], v[162:165], v[208:211], v[100:103]
	v_mfma_f32_16x16x32_bf16 v[96:99], v[192:195], v[208:211], v[96:99]
	v_mfma_f32_16x16x32_bf16 v[84:87], v[162:165], v[216:219], v[84:87]
	s_add_i32 s59, s59, s7
	v_mfma_f32_16x16x32_bf16 v[80:83], v[192:195], v[216:219], v[80:83]
	v_lshl_add_u64 v[166:167], s[38:39], 0, v[168:169]
	v_mfma_f32_16x16x32_bf16 v[68:71], v[162:165], v[234:237], v[68:71]
	s_mov_b32 m0, s59
	v_mfma_f32_16x16x32_bf16 v[64:67], v[192:195], v[234:237], v[64:67]
	s_setprio 0
	s_barrier
	ds_read_b128 v[196:199], v145 offset:16384
	ds_read_b128 v[200:203], v145 offset:17408
	ds_read_b128 v[204:207], v145 offset:18432
	ds_read_b128 v[208:211], v145 offset:19456
	ds_read_b128 v[212:215], v145 offset:20480
	ds_read_b128 v[216:219], v145 offset:21504
	ds_read_b128 v[220:223], v145 offset:22528
	ds_read_b128 v[234:237], v145 offset:23552
	global_load_lds_dwordx4 v[166:167], off
	s_add_i32 m0, s59, 0x2000
	s_add_u32 s60, s38, 0x40000
	v_lshl_add_u64 v[170:171], s[38:39], 0, v[128:129]
	s_addc_u32 s61, s39, 0
	s_add_i32 s59, s62, s7
	global_load_lds_dwordx4 v[170:171], off
	v_lshl_add_u64 v[172:173], s[60:61], 0, v[168:169]
	s_mov_b32 m0, s59
	v_lshl_add_u64 v[224:225], s[46:47], 0, v[130:131]
	global_load_lds_dwordx4 v[172:173], off
	v_lshl_add_u64 v[172:173], s[60:61], 0, v[128:129]
	s_add_i32 m0, s59, 0x2000
	s_nop 0
	global_load_lds_dwordx4 v[172:173], off
	v_lshl_add_u64 v[172:173], s[46:47], 0, v[132:133]
	s_mov_b32 m0, s2
	s_nop 0
	global_load_lds_dwordx4 v[172:173], off
	s_mov_b32 m0, s34
	s_nop 0
	global_load_lds_dwordx4 v[224:225], off
	s_waitcnt vmcnt(8)
	s_waitcnt lgkmcnt(0)
	s_barrier
	s_setprio 1
	v_mfma_f32_16x16x32_bf16 v[60:63], v[138:141], v[196:199], 0
	v_mfma_f32_16x16x32_bf16 v[56:59], v[150:153], v[196:199], 0
	v_mfma_f32_16x16x32_bf16 v[44:47], v[138:141], v[204:207], 0
	v_mfma_f32_16x16x32_bf16 v[40:43], v[150:153], v[204:207], 0
	v_mfma_f32_16x16x32_bf16 v[28:31], v[138:141], v[212:215], 0
	v_mfma_f32_16x16x32_bf16 v[24:27], v[150:153], v[212:215], 0
	v_mfma_f32_16x16x32_bf16 v[12:15], v[138:141], v[220:223], 0
	v_mfma_f32_16x16x32_bf16 v[8:11], v[150:153], v[220:223], 0
	v_mfma_f32_16x16x32_bf16 v[60:63], v[146:149], v[200:203], v[60:63]
	v_mfma_f32_16x16x32_bf16 v[56:59], v[154:157], v[200:203], v[56:59]
	v_mfma_f32_16x16x32_bf16 v[44:47], v[146:149], v[208:211], v[44:47]
	v_mfma_f32_16x16x32_bf16 v[40:43], v[154:157], v[208:211], v[40:43]
	v_mfma_f32_16x16x32_bf16 v[28:31], v[146:149], v[216:219], v[28:31]
	v_mfma_f32_16x16x32_bf16 v[24:27], v[154:157], v[216:219], v[24:27]
	v_mfma_f32_16x16x32_bf16 v[12:15], v[146:149], v[234:237], v[12:15]
	v_mfma_f32_16x16x32_bf16 v[8:11], v[154:157], v[234:237], v[8:11]
	s_setprio 0
	s_setprio 1
	v_mfma_f32_16x16x32_bf16 v[52:55], v[158:161], v[196:199], 0
	v_mfma_f32_16x16x32_bf16 v[48:51], v[188:191], v[196:199], 0
	v_mfma_f32_16x16x32_bf16 v[36:39], v[158:161], v[204:207], 0
	v_mfma_f32_16x16x32_bf16 v[32:35], v[188:191], v[204:207], 0
	v_mfma_f32_16x16x32_bf16 v[20:23], v[158:161], v[212:215], 0
	v_mfma_f32_16x16x32_bf16 v[16:19], v[188:191], v[212:215], 0
	v_mfma_f32_16x16x32_bf16 v[4:7], v[158:161], v[220:223], 0
	v_mfma_f32_16x16x32_bf16 v[0:3], v[188:191], v[220:223], 0
	v_mfma_f32_16x16x32_bf16 v[52:55], v[162:165], v[200:203], v[52:55]
	v_mfma_f32_16x16x32_bf16 v[48:51], v[192:195], v[200:203], v[48:51]
	v_mfma_f32_16x16x32_bf16 v[36:39], v[162:165], v[208:211], v[36:39]
	v_mfma_f32_16x16x32_bf16 v[32:35], v[192:195], v[208:211], v[32:35]
	s_add_i32 s59, 0, 0x18000
	v_mfma_f32_16x16x32_bf16 v[20:23], v[162:165], v[216:219], v[20:23]
	s_add_i32 s60, 0, 0x1c000
	v_mfma_f32_16x16x32_bf16 v[16:19], v[192:195], v[216:219], v[16:19]
	v_add_u32_e32 v240, s59, v143
	v_mfma_f32_16x16x32_bf16 v[4:7], v[162:165], v[234:237], v[4:7]
	v_add_u32_e32 v178, s60, v143
	v_mfma_f32_16x16x32_bf16 v[0:3], v[192:195], v[234:237], v[0:3]
	s_setprio 0
	s_barrier
; #define PG8_STAGE(bufoff, gbase, voff) do { _Pragma("unroll") for (int _i = 0; _i < 2; ++_i) \
;         __builtin_amdgcn_global_load_lds((const unsigned*)((const char*)(gbase) + (voff)[_i]), (PG8_LAS unsigned*)(lds + (bufoff) + ldsw + _i * 8192), 16, 0, 0); } while (0)
; #define PG8_LDA(dst, b, h) do { _Pragma("unroll") for (int m = 0; m < 4; ++m) _Pragma("unroll") for (int k = 0; k < 2; ++k) dst[m][k] = *(const PG8_LAS bf16x8*)(lds + PG8_SA(b, h) + aoff + m * 2048 + k * 1024); } while (0)
; #define PG8_LDB(dst, b, h) do { _Pragma("unroll") for (int n = 0; n < 2; ++n) _Pragma("unroll") for (int k = 0; k < 2; ++k) dst[n][k] = *(const PG8_LAS bf16x8*)(lds + PG8_SB(b, h) + boff + n * 2048 + k * 1024); } while (0)
; #define PG8_MMA(ai, bj, At, Bt) do { __builtin_amdgcn_s_setprio(1); _Pragma("unroll") for (int m = 0; m < 4; ++m) _Pragma("unroll") for (int n = 0; n < 2; ++n) _Pragma("unroll") for (int k = 0; k < 2; ++k) \
;         acc[ai][bj][m][n] = __builtin_amdgcn_mfma_f32_16x16x32_bf16(Bt[n][k], At[m][k], acc[ai][bj][m][n], 0, 0, 0); __builtin_amdgcn_s_setprio(0); } while (0)
; #define PG8_WAIT_V(n) asm volatile("s_waitcnt vmcnt(" #n ")" ::: "memory")
; #define PG8_WAIT_L(n) asm volatile("s_waitcnt lgkmcnt(" #n ")" ::: "memory")
; #define PG8_BAR __builtin_amdgcn_s_barrier()
; #define PG8_SCHED __builtin_amdgcn_sched_barrier(0)
; template <class Epi, class Sched, bool ALIGN_EPI = false, bool SP2 = false>
; __device__ __forceinline__ void gemm_phase(PG8_LAS unsigned char* lds, const Gemm g, const Sched& S, const Epi& E) {
;     ...
;             PG8_LDB(B0, 1, 0); PG8_LDB(B1, 1, 1); PG8_SCHED; PG8_LDA(At, 1, 0); PG8_STAGE(PG8_SA(0, 1), a2 + hstepA, voffA);
;             PG8_WAIT_V(8); PG8_WAIT_L(0); PG8_BAR; PG8_MMA(0, 0, At, B0); PG8_MMA(0, 1, At, B1); PG8_BAR; PG8_SCHED;
	ds_read_b128 v[138:141], v240
	ds_read_b128 v[146:149], v240 offset:1024
	ds_read_b128 v[150:153], v240 offset:2048
	ds_read_b128 v[154:157], v240 offset:3072
	ds_read_b128 v[158:161], v178
	ds_read_b128 v[162:165], v178 offset:1024
	ds_read_b128 v[188:191], v178 offset:2048
	ds_read_b128 v[192:195], v178 offset:3072
	ds_read_b128 v[196:199], v145 offset:32768
	ds_read_b128 v[200:203], v145 offset:33792
	ds_read_b128 v[204:207], v145 offset:34816
	ds_read_b128 v[208:211], v145 offset:35840
	ds_read_b128 v[212:215], v145 offset:36864
	ds_read_b128 v[216:219], v145 offset:37888
	ds_read_b128 v[220:223], v145 offset:38912
	ds_read_b128 v[234:237], v145 offset:39936
	s_add_u32 s46, s46, 0x40000
	s_addc_u32 s47, s47, 0
	s_mov_b32 m0, s35
	v_lshl_add_u64 v[238:239], s[46:47], 0, v[132:133]
	global_load_lds_dwordx4 v[238:239], off
	v_lshl_add_u64 v[238:239], s[46:47], 0, v[130:131]
	s_mov_b32 m0, s48
	s_nop 0
	global_load_lds_dwordx4 v[238:239], off
	s_waitcnt vmcnt(8)
	s_waitcnt lgkmcnt(0)
	s_barrier
	s_setprio 1
	v_mfma_f32_16x16x32_bf16 v[124:127], v[138:141], v[196:199], v[124:127]
	v_mfma_f32_16x16x32_bf16 v[120:123], v[150:153], v[196:199], v[120:123]
	v_mfma_f32_16x16x32_bf16 v[108:111], v[138:141], v[204:207], v[108:111]
	v_mfma_f32_16x16x32_bf16 v[104:107], v[150:153], v[204:207], v[104:107]
	v_mfma_f32_16x16x32_bf16 v[92:95], v[138:141], v[212:215], v[92:95]
	v_mfma_f32_16x16x32_bf16 v[88:91], v[150:153], v[212:215], v[88:91]
	v_mfma_f32_16x16x32_bf16 v[76:79], v[138:141], v[220:223], v[76:79]
	v_mfma_f32_16x16x32_bf16 v[72:75], v[150:153], v[220:223], v[72:75]
	v_mfma_f32_16x16x32_bf16 v[124:127], v[146:149], v[200:203], v[124:127]
	v_mfma_f32_16x16x32_bf16 v[120:123], v[154:157], v[200:203], v[120:123]
	v_mfma_f32_16x16x32_bf16 v[108:111], v[146:149], v[208:211], v[108:111]
	v_mfma_f32_16x16x32_bf16 v[104:107], v[154:157], v[208:211], v[104:107]
	v_mfma_f32_16x16x32_bf16 v[92:95], v[146:149], v[216:219], v[92:95]
	v_mfma_f32_16x16x32_bf16 v[88:91], v[154:157], v[216:219], v[88:91]
	v_mfma_f32_16x16x32_bf16 v[76:79], v[146:149], v[234:237], v[76:79]
	v_mfma_f32_16x16x32_bf16 v[72:75], v[154:157], v[234:237], v[72:75]
	s_setprio 0
	s_setprio 1
	v_mfma_f32_16x16x32_bf16 v[116:119], v[158:161], v[196:199], v[116:119]
	v_mfma_f32_16x16x32_bf16 v[112:115], v[188:191], v[196:199], v[112:115]
	v_mfma_f32_16x16x32_bf16 v[100:103], v[158:161], v[204:207], v[100:103]
	v_mfma_f32_16x16x32_bf16 v[96:99], v[188:191], v[204:207], v[96:99]
	v_mfma_f32_16x16x32_bf16 v[84:87], v[158:161], v[212:215], v[84:87]
	v_mfma_f32_16x16x32_bf16 v[80:83], v[188:191], v[212:215], v[80:83]
	v_mfma_f32_16x16x32_bf16 v[68:71], v[158:161], v[220:223], v[68:71]
	v_mfma_f32_16x16x32_bf16 v[64:67], v[188:191], v[220:223], v[64:67]
	v_mfma_f32_16x16x32_bf16 v[116:119], v[162:165], v[200:203], v[116:119]
	v_mfma_f32_16x16x32_bf16 v[112:115], v[192:195], v[200:203], v[112:115]
	v_mfma_f32_16x16x32_bf16 v[100:103], v[162:165], v[208:211], v[100:103]
	v_mfma_f32_16x16x32_bf16 v[96:99], v[192:195], v[208:211], v[96:99]
	v_mfma_f32_16x16x32_bf16 v[84:87], v[162:165], v[216:219], v[84:87]
	s_add_i32 s46, s59, s7
	v_mfma_f32_16x16x32_bf16 v[80:83], v[192:195], v[216:219], v[80:83]
	v_lshl_add_u64 v[166:167], v[166:167], 0, s[30:31]
	v_mfma_f32_16x16x32_bf16 v[68:71], v[162:165], v[234:237], v[68:71]
	s_mov_b32 m0, s46
	v_mfma_f32_16x16x32_bf16 v[64:67], v[192:195], v[234:237], v[64:67]
	s_setprio 0
	s_barrier
; #define PG8_STAGE(bufoff, gbase, voff) do { _Pragma("unroll") for (int _i = 0; _i < 2; ++_i) \
;         __builtin_amdgcn_global_load_lds((const unsigned*)((const char*)(gbase) + (voff)[_i]), (PG8_LAS unsigned*)(lds + (bufoff) + ldsw + _i * 8192), 16, 0, 0); } while (0)
; #define PG8_LDA(dst, b, h) do { _Pragma("unroll") for (int m = 0; m < 4; ++m) _Pragma("unroll") for (int k = 0; k < 2; ++k) dst[m][k] = *(const PG8_LAS bf16x8*)(lds + PG8_SA(b, h) + aoff + m * 2048 + k * 1024); } while (0)
; #define PG8_LDB(dst, b, h) do { _Pragma("unroll") for (int n = 0; n < 2; ++n) _Pragma("unroll") for (int k = 0; k < 2; ++k) dst[n][k] = *(const PG8_LAS bf16x8*)(lds + PG8_SB(b, h) + boff + n * 2048 + k * 1024); } while (0)
; template <class Epi, class Sched, bool ALIGN_EPI = false, bool SP2 = false>
; __device__ __forceinline__ void gemm_phase(PG8_LAS unsigned char* lds, const Gemm g, const Sched& S, const Epi& E) {
;     ...
;         for (int t = 0; t < nt; t += 2) {
;             const bool last = (t == nt - 2);
;             const char* a1 = cA + (size_t)(t + 1) * kstepA;
;             const char* a2 = last ? nA : cA + (size_t)(t + 2) * kstepA; const char* b2 = last ? nB : cB + (size_t)(t + 2) * kstep;
;             const char* a3 = a2 + kstepA; const char* b3 = b2 + kstep;
;             if (last && has_next) S.a_ready(nxt);
;             if constexpr (SP2) {
;             PG8_LDB(B0, 0, 0); PG8_LDB(B1, 0, 1); PG8_SCHED; PG8_LDA(At, 0, 0); PG8_STAGE(PG8_SA(1, 1), a1 + hstepA, voffA);
;             PG8_WAIT_V(8); PG8_WAIT_L(0); PG8_BAR; PG8_MMA(0, 0, At, B0); PG8_MMA(0, 1, At, B1); PG8_BAR; PG8_SCHED;
;             PG8_LDA(At, 0, 1); PG8_STAGE(PG8_SB(0, 0), b2, voffB); PG8_STAGE(PG8_SB(0, 1), b2 + hstep, voffB); PG8_STAGE(PG8_SA(0, 0), a2, voffA);
;             PG8_WAIT_V(8); PG8_WAIT_L(0); PG8_BAR; PG8_MMA(1, 0, At, B0); PG8_MMA(1, 1, At, B1); PG8_BAR; PG8_SCHED;
;             PG8_LDB(B0, 1, 0); PG8_LDB(B1, 1, 1); PG8_SCHED; PG8_LDA(At, 1, 0); PG8_STAGE(PG8_SA(0, 1), a2 + hstepA, voffA);
;             PG8_WAIT_V(8); PG8_WAIT_L(0); PG8_BAR; PG8_MMA(0, 0, At, B0); PG8_MMA(0, 1, At, B1); PG8_BAR; PG8_SCHED;
;             PG8_LDA(At, 1, 1); PG8_STAGE(PG8_SB(1, 0), b3, voffB); PG8_STAGE(PG8_SB(1, 1), b3 + hstep, voffB); PG8_STAGE(PG8_SA(1, 0), a3, voffA);
;             PG8_WAIT_V(8); PG8_WAIT_L(0); PG8_BAR; PG8_MMA(1, 0, At, B0); PG8_MMA(1, 1, At, B1); PG8_BAR; PG8_SCHED;
	ds_read_b128 v[196:199], v145 offset:49152
	ds_read_b128 v[200:203], v145 offset:50176
	ds_read_b128 v[204:207], v145 offset:51200
	ds_read_b128 v[208:211], v145 offset:52224
	ds_read_b128 v[212:215], v145 offset:53248
	ds_read_b128 v[216:219], v145 offset:54272
	ds_read_b128 v[220:223], v145 offset:55296
	ds_read_b128 v[234:237], v145 offset:56320
	global_load_lds_dwordx4 v[166:167], off
	s_add_i32 m0, s46, 0x2000
	s_add_u32 s38, s38, 0x40080
	v_lshl_add_u64 v[166:167], v[170:171], 0, s[30:31]
	s_addc_u32 s39, s39, 0
	s_add_i32 s46, s60, s7
	global_load_lds_dwordx4 v[166:167], off
	v_lshl_add_u64 v[166:167], s[38:39], 0, v[168:169]
	s_mov_b32 m0, s46
	s_nop 0
	global_load_lds_dwordx4 v[166:167], off
	v_lshl_add_u64 v[166:167], s[38:39], 0, v[128:129]
	s_add_i32 m0, s46, 0x2000
	s_nop 0
	global_load_lds_dwordx4 v[166:167], off
	v_lshl_add_u64 v[166:167], v[172:173], 0, s[30:31]
	s_mov_b32 m0, s49
	s_nop 0
	global_load_lds_dwordx4 v[166:167], off
	v_lshl_add_u64 v[166:167], v[224:225], 0, s[30:31]
	s_mov_b32 m0, s50
	s_nop 0
	global_load_lds_dwordx4 v[166:167], off
	s_waitcnt vmcnt(8)
	s_waitcnt lgkmcnt(0)
	s_barrier
	s_setprio 1
	v_mfma_f32_16x16x32_bf16 v[60:63], v[138:141], v[196:199], v[60:63]
	v_mfma_f32_16x16x32_bf16 v[56:59], v[150:153], v[196:199], v[56:59]
	v_mfma_f32_16x16x32_bf16 v[44:47], v[138:141], v[204:207], v[44:47]
	v_mfma_f32_16x16x32_bf16 v[40:43], v[150:153], v[204:207], v[40:43]
	v_mfma_f32_16x16x32_bf16 v[28:31], v[138:141], v[212:215], v[28:31]
	v_mfma_f32_16x16x32_bf16 v[24:27], v[150:153], v[212:215], v[24:27]
	v_mfma_f32_16x16x32_bf16 v[12:15], v[138:141], v[220:223], v[12:15]
	v_mfma_f32_16x16x32_bf16 v[8:11], v[150:153], v[220:223], v[8:11]
	v_mfma_f32_16x16x32_bf16 v[60:63], v[146:149], v[200:203], v[60:63]
	v_mfma_f32_16x16x32_bf16 v[56:59], v[154:157], v[200:203], v[56:59]
	v_mfma_f32_16x16x32_bf16 v[44:47], v[146:149], v[208:211], v[44:47]
	v_mfma_f32_16x16x32_bf16 v[40:43], v[154:157], v[208:211], v[40:43]
	v_mfma_f32_16x16x32_bf16 v[28:31], v[146:149], v[216:219], v[28:31]
	v_mfma_f32_16x16x32_bf16 v[24:27], v[154:157], v[216:219], v[24:27]
	v_mfma_f32_16x16x32_bf16 v[12:15], v[146:149], v[234:237], v[12:15]
	v_mfma_f32_16x16x32_bf16 v[8:11], v[154:157], v[234:237], v[8:11]
	s_add_i32 s58, s58, 2
	s_setprio 0
	s_setprio 1
	v_mfma_f32_16x16x32_bf16 v[52:55], v[158:161], v[196:199], v[52:55]
	s_add_u32 s56, s56, 0x100
	v_mfma_f32_16x16x32_bf16 v[48:51], v[188:191], v[196:199], v[48:51]
	s_addc_u32 s57, s57, 0
	v_mfma_f32_16x16x32_bf16 v[36:39], v[158:161], v[204:207], v[36:39]
	s_add_u32 s4, s4, 0x100
	v_mfma_f32_16x16x32_bf16 v[32:35], v[188:191], v[204:207], v[32:35]
	s_addc_u32 s5, s5, 0
	v_mfma_f32_16x16x32_bf16 v[20:23], v[158:161], v[212:215], v[20:23]
	s_add_u32 s38, s4, 0xfffc0080
	v_mfma_f32_16x16x32_bf16 v[16:19], v[188:191], v[212:215], v[16:19]
	s_addc_u32 s39, s5, -1
	v_mfma_f32_16x16x32_bf16 v[4:7], v[158:161], v[220:223], v[4:7]
	s_add_i32 s59, 0, 0x10000
	v_mfma_f32_16x16x32_bf16 v[0:3], v[188:191], v[220:223], v[0:3]
	s_cmp_eq_u32 s58, 12
	v_mfma_f32_16x16x32_bf16 v[52:55], v[162:165], v[200:203], v[52:55]
	s_cselect_b32 s47, s41, s39
	v_mfma_f32_16x16x32_bf16 v[48:51], v[192:195], v[200:203], v[48:51]
	s_cselect_b32 s46, s54, s38
	v_mfma_f32_16x16x32_bf16 v[36:39], v[162:165], v[208:211], v[36:39]
	s_cselect_b32 s39, s27, s57
	v_mfma_f32_16x16x32_bf16 v[32:35], v[192:195], v[208:211], v[32:35]
	s_cselect_b32 s38, s55, s56
	v_mfma_f32_16x16x32_bf16 v[20:23], v[162:165], v[216:219], v[20:23]
	s_add_i32 s62, 0, 0x14000
	v_mfma_f32_16x16x32_bf16 v[16:19], v[192:195], v[216:219], v[16:19]
	v_add_u32_e32 v241, s59, v143
	v_mfma_f32_16x16x32_bf16 v[4:7], v[162:165], v[234:237], v[4:7]
	v_add_u32_e32 v166, s62, v143
	v_mfma_f32_16x16x32_bf16 v[0:3], v[192:195], v[234:237], v[0:3]
	s_setprio 0
	s_barrier
	.p2align	6

; #define PG8_STAGE(bufoff, gbase, voff) do { _Pragma("unroll") for (int _i = 0; _i < 2; ++_i) \
;         __builtin_amdgcn_global_load_lds((const unsigned*)((const char*)(gbase) + (voff)[_i]), (PG8_LAS unsigned*)(lds + (bufoff) + ldsw + _i * 8192), 16, 0, 0); } while (0)
; #define PG8_LDA(dst, b, h) do { _Pragma("unroll") for (int m = 0; m < 4; ++m) _Pragma("unroll") for (int k = 0; k < 2; ++k) dst[m][k] = *(const PG8_LAS bf16x8*)(lds + PG8_SA(b, h) + aoff + m * 2048 + k * 1024); } while (0)
; #define PG8_BAR __builtin_amdgcn_s_barrier()
; template <class Epi, class Sched, bool ALIGN_EPI = false, bool SP2 = false>
; __device__ __forceinline__ void gemm_phase(PG8_LAS unsigned char* lds, const Gemm g, const Sched& S, const Epi& E) {
;     ...
;         const char* nA = has_next ? (const char*)g.A + (size_t)nxt.pm * tstepA : cA; const char* nB = has_next ? (const char*)g.Bt + (size_t)nxt.pn * tstep : cB;
;         for (int t = 0; t < nt; t += 2) {
;             const bool last = (t == nt - 2);
;             const char* a1 = cA + (size_t)(t + 1) * kstepA;
;             const char* a2 = last ? nA : cA + (size_t)(t + 2) * kstepA; const char* b2 = last ? nB : cB + (size_t)(t + 2) * kstep;
;             const char* a3 = a2 + kstepA; const char* b3 = b2 + kstep;
;             if (last && has_next) S.a_ready(nxt);
;             if constexpr (SP2) {
;             PG8_LDB(B0, 0, 0); PG8_LDB(B1, 0, 1); PG8_SCHED; PG8_LDA(At, 0, 0); PG8_STAGE(PG8_SA(1, 1), a1 + hstepA, voffA);
;             PG8_WAIT_V(8); PG8_WAIT_L(0); PG8_BAR; PG8_MMA(0, 0, At, B0); PG8_MMA(0, 1, At, B1); PG8_BAR; PG8_SCHED;
;             PG8_LDA(At, 0, 1); PG8_STAGE(PG8_SB(0, 0), b2, voffB); PG8_STAGE(PG8_SB(0, 1), b2 + hstep, voffB); PG8_STAGE(PG8_SA(0, 0), a2, voffA);
;             PG8_WAIT_V(8); PG8_WAIT_L(0); PG8_BAR; PG8_MMA(1, 0, At, B0); PG8_MMA(1, 1, At, B1); PG8_BAR; PG8_SCHED;
;             PG8_LDB(B0, 1, 0); PG8_LDB(B1, 1, 1); PG8_SCHED; PG8_LDA(At, 1, 0); PG8_STAGE(PG8_SA(0, 1), a2 + hstepA, voffA);
;             PG8_WAIT_V(8); PG8_WAIT_L(0); PG8_BAR; PG8_MMA(0, 0, At, B0); PG8_MMA(0, 1, At, B1); PG8_BAR; PG8_SCHED;
;             PG8_LDA(At, 1, 1); PG8_STAGE(PG8_SB(1, 0), b3, voffB); PG8_STAGE(PG8_SB(1, 1), b3 + hstep, voffB); PG8_STAGE(PG8_SA(1, 0), a3, voffA);
;             PG8_WAIT_V(8); PG8_WAIT_L(0); PG8_BAR; PG8_MMA(1, 0, At, B0); PG8_MMA(1, 1, At, B1); PG8_BAR; PG8_SCHED;
.LBB0_732:
	s_ashr_i32 s53, s52, 31
	s_lshl_b64 s[6:7], s[52:53], 19
	s_add_u32 s54, s78, s6
	s_addc_u32 s55, s79, s7
	s_and_b64 s[6:7], s[38:39], exec
	s_cselect_b32 s5, s55, s37
	s_cselect_b32 s6, s54, s36
	s_ashr_i32 s51, s50, 31
	s_lshl_b64 s[56:57], s[50:51], 19
	s_add_u32 s56, s2, s56
	s_addc_u32 s57, s3, s57
	s_and_b64 s[60:61], s[38:39], exec
	s_cselect_b32 s7, s57, s41
	s_cselect_b32 s51, s56, s40
	s_add_u32 s53, s40, 0x100
	s_addc_u32 s64, s41, 0
	s_add_u32 s40, s36, 0x40080
	s_addc_u32 s41, s37, 0
	s_mov_b32 s65, -2
	s_add_u32 s58, s40, 0xfffc0080
	s_addc_u32 s59, s41, -1
	s_add_i32 s74, 0, 0x10000
	s_cmp_eq_u32 s65, 12
	s_cselect_b32 s61, s5, s59
	s_cselect_b32 s60, s6, s58
	s_cselect_b32 s59, s7, s64
	s_cselect_b32 s58, s51, s53
	s_add_i32 s91, 0, 0x14000
	s_add_i32 m0, s35, 0xc000
	v_lshl_add_u64 v[178:179], s[40:41], 0, v[196:197]
	global_load_lds_dwordx4 v[178:179], off
	v_lshl_add_u64 v[178:179], s[40:41], 0, v[194:195]
	s_add_i32 m0, s35, 0xe000
	s_nop 0
	global_load_lds_dwordx4 v[178:179], off
	s_waitcnt vmcnt(8)
	s_waitcnt lgkmcnt(0)
	s_barrier
	s_setprio 1
	v_mfma_f32_16x16x32_bf16 v[124:127], v[128:131], v[160:163], 0
	v_mfma_f32_16x16x32_bf16 v[120:123], v[136:139], v[160:163], 0
	v_mfma_f32_16x16x32_bf16 v[108:111], v[128:131], v[170:173], 0
	v_mfma_f32_16x16x32_bf16 v[104:107], v[136:139], v[170:173], 0
	v_mfma_f32_16x16x32_bf16 v[92:95], v[128:131], v[202:205], 0
	v_mfma_f32_16x16x32_bf16 v[88:91], v[136:139], v[202:205], 0
	v_mfma_f32_16x16x32_bf16 v[76:79], v[128:131], v[210:213], 0
	v_mfma_f32_16x16x32_bf16 v[72:75], v[136:139], v[210:213], 0
	v_mfma_f32_16x16x32_bf16 v[124:127], v[132:135], v[164:167], v[124:127]
	v_mfma_f32_16x16x32_bf16 v[120:123], v[140:143], v[164:167], v[120:123]
	v_mfma_f32_16x16x32_bf16 v[108:111], v[132:135], v[198:201], v[108:111]
	v_mfma_f32_16x16x32_bf16 v[104:107], v[140:143], v[198:201], v[104:107]
	v_mfma_f32_16x16x32_bf16 v[92:95], v[132:135], v[206:209], v[92:95]
	v_mfma_f32_16x16x32_bf16 v[88:91], v[140:143], v[206:209], v[88:91]
	v_mfma_f32_16x16x32_bf16 v[76:79], v[132:135], v[214:217], v[76:79]
	v_mfma_f32_16x16x32_bf16 v[72:75], v[140:143], v[214:217], v[72:75]
	s_setprio 0
	s_setprio 1
	v_mfma_f32_16x16x32_bf16 v[116:119], v[144:147], v[160:163], 0
	v_mfma_f32_16x16x32_bf16 v[112:115], v[152:155], v[160:163], 0
	v_mfma_f32_16x16x32_bf16 v[100:103], v[144:147], v[170:173], 0
	v_mfma_f32_16x16x32_bf16 v[96:99], v[152:155], v[170:173], 0
	v_mfma_f32_16x16x32_bf16 v[84:87], v[144:147], v[202:205], 0
	v_mfma_f32_16x16x32_bf16 v[80:83], v[152:155], v[202:205], 0
	v_mfma_f32_16x16x32_bf16 v[68:71], v[144:147], v[210:213], 0
	v_mfma_f32_16x16x32_bf16 v[64:67], v[152:155], v[210:213], 0
	v_mfma_f32_16x16x32_bf16 v[116:119], v[148:151], v[164:167], v[116:119]
	v_mfma_f32_16x16x32_bf16 v[112:115], v[156:159], v[164:167], v[112:115]
	v_mfma_f32_16x16x32_bf16 v[100:103], v[148:151], v[198:201], v[100:103]
	v_mfma_f32_16x16x32_bf16 v[96:99], v[156:159], v[198:201], v[96:99]
	v_mfma_f32_16x16x32_bf16 v[84:87], v[148:151], v[206:209], v[84:87]
	s_add_i32 s74, s74, s34
	v_mfma_f32_16x16x32_bf16 v[80:83], v[156:159], v[206:209], v[80:83]
	v_lshl_add_u64 v[178:179], s[58:59], 0, v[168:169]
	v_mfma_f32_16x16x32_bf16 v[68:71], v[148:151], v[214:217], v[68:71]
	s_mov_b32 m0, s74
	v_mfma_f32_16x16x32_bf16 v[64:67], v[156:159], v[214:217], v[64:67]
	s_setprio 0
	s_barrier
	ds_read_b128 v[160:163], v225 offset:16384
	ds_read_b128 v[164:167], v225 offset:17408
	ds_read_b128 v[170:173], v225 offset:18432
	ds_read_b128 v[198:201], v225 offset:19456
	ds_read_b128 v[202:205], v225 offset:20480
	ds_read_b128 v[206:209], v225 offset:21504
	ds_read_b128 v[210:213], v225 offset:22528
	ds_read_b128 v[214:217], v225 offset:23552
	global_load_lds_dwordx4 v[178:179], off
	s_add_i32 m0, s74, 0x2000
	s_add_u32 s74, s58, 0x40000
	v_lshl_add_u64 v[218:219], s[58:59], 0, v[188:189]
	s_addc_u32 s75, s59, 0
	s_add_i32 s91, s91, s34
	global_load_lds_dwordx4 v[218:219], off
	v_lshl_add_u64 v[220:221], s[74:75], 0, v[168:169]
	s_mov_b32 m0, s91
	v_lshl_add_u64 v[234:235], s[60:61], 0, v[190:191]
	global_load_lds_dwordx4 v[220:221], off
	v_lshl_add_u64 v[220:221], s[74:75], 0, v[188:189]
	s_add_i32 m0, s91, 0x2000
	s_nop 0
	global_load_lds_dwordx4 v[220:221], off
	v_lshl_add_u64 v[220:221], s[60:61], 0, v[192:193]
	s_mov_b32 m0, s35
	s_nop 0
	global_load_lds_dwordx4 v[220:221], off
	s_mov_b32 m0, s69
	s_nop 0
	global_load_lds_dwordx4 v[234:235], off
	s_waitcnt vmcnt(8)
	s_waitcnt lgkmcnt(0)
	s_barrier
	s_setprio 1
	v_mfma_f32_16x16x32_bf16 v[60:63], v[128:131], v[160:163], 0
	v_mfma_f32_16x16x32_bf16 v[56:59], v[136:139], v[160:163], 0
	v_mfma_f32_16x16x32_bf16 v[44:47], v[128:131], v[170:173], 0
	v_mfma_f32_16x16x32_bf16 v[40:43], v[136:139], v[170:173], 0
	v_mfma_f32_16x16x32_bf16 v[28:31], v[128:131], v[202:205], 0
	v_mfma_f32_16x16x32_bf16 v[24:27], v[136:139], v[202:205], 0
	v_mfma_f32_16x16x32_bf16 v[12:15], v[128:131], v[210:213], 0
	v_mfma_f32_16x16x32_bf16 v[8:11], v[136:139], v[210:213], 0
	v_mfma_f32_16x16x32_bf16 v[60:63], v[132:135], v[164:167], v[60:63]
	v_mfma_f32_16x16x32_bf16 v[56:59], v[140:143], v[164:167], v[56:59]
	v_mfma_f32_16x16x32_bf16 v[44:47], v[132:135], v[198:201], v[44:47]
	v_mfma_f32_16x16x32_bf16 v[40:43], v[140:143], v[198:201], v[40:43]
	v_mfma_f32_16x16x32_bf16 v[28:31], v[132:135], v[206:209], v[28:31]
	v_mfma_f32_16x16x32_bf16 v[24:27], v[140:143], v[206:209], v[24:27]
	v_mfma_f32_16x16x32_bf16 v[12:15], v[132:135], v[214:217], v[12:15]
	v_mfma_f32_16x16x32_bf16 v[8:11], v[140:143], v[214:217], v[8:11]
	s_setprio 0
	s_setprio 1
	v_mfma_f32_16x16x32_bf16 v[52:55], v[144:147], v[160:163], 0
	v_mfma_f32_16x16x32_bf16 v[48:51], v[152:155], v[160:163], 0
	v_mfma_f32_16x16x32_bf16 v[36:39], v[144:147], v[170:173], 0
	v_mfma_f32_16x16x32_bf16 v[32:35], v[152:155], v[170:173], 0
	v_mfma_f32_16x16x32_bf16 v[20:23], v[144:147], v[202:205], 0
	v_mfma_f32_16x16x32_bf16 v[16:19], v[152:155], v[202:205], 0
	v_mfma_f32_16x16x32_bf16 v[4:7], v[144:147], v[210:213], 0
	v_mfma_f32_16x16x32_bf16 v[0:3], v[152:155], v[210:213], 0
	v_mfma_f32_16x16x32_bf16 v[52:55], v[148:151], v[164:167], v[52:55]
	v_mfma_f32_16x16x32_bf16 v[48:51], v[156:159], v[164:167], v[48:51]
	v_mfma_f32_16x16x32_bf16 v[36:39], v[148:151], v[198:201], v[36:39]
	v_mfma_f32_16x16x32_bf16 v[32:35], v[156:159], v[198:201], v[32:35]
	s_add_i32 s74, 0, 0x18000
	v_mfma_f32_16x16x32_bf16 v[20:23], v[148:151], v[206:209], v[20:23]
	s_add_i32 s75, 0, 0x1c000
	v_mfma_f32_16x16x32_bf16 v[16:19], v[156:159], v[206:209], v[16:19]
	v_add_u32_e32 v240, s74, v224
	v_mfma_f32_16x16x32_bf16 v[4:7], v[148:151], v[214:217], v[4:7]
	v_add_u32_e32 v241, s75, v224
	v_mfma_f32_16x16x32_bf16 v[0:3], v[156:159], v[214:217], v[0:3]
	s_setprio 0
	s_barrier
; #define PG8_STAGE(bufoff, gbase, voff) do { _Pragma("unroll") for (int _i = 0; _i < 2; ++_i) \
;         __builtin_amdgcn_global_load_lds((const unsigned*)((const char*)(gbase) + (voff)[_i]), (PG8_LAS unsigned*)(lds + (bufoff) + ldsw + _i * 8192), 16, 0, 0); } while (0)
; #define PG8_LDA(dst, b, h) do { _Pragma("unroll") for (int m = 0; m < 4; ++m) _Pragma("unroll") for (int k = 0; k < 2; ++k) dst[m][k] = *(const PG8_LAS bf16x8*)(lds + PG8_SA(b, h) + aoff + m * 2048 + k * 1024); } while (0)
; #define PG8_LDB(dst, b, h) do { _Pragma("unroll") for (int n = 0; n < 2; ++n) _Pragma("unroll") for (int k = 0; k < 2; ++k) dst[n][k] = *(const PG8_LAS bf16x8*)(lds + PG8_SB(b, h) + boff + n * 2048 + k * 1024); } while (0)
; #define PG8_MMA(ai, bj, At, Bt) do { __builtin_amdgcn_s_setprio(1); _Pragma("unroll") for (int m = 0; m < 4; ++m) _Pragma("unroll") for (int n = 0; n < 2; ++n) _Pragma("unroll") for (int k = 0; k < 2; ++k) \
;         acc[ai][bj][m][n] = __builtin_amdgcn_mfma_f32_16x16x32_bf16(Bt[n][k], At[m][k], acc[ai][bj][m][n], 0, 0, 0); __builtin_amdgcn_s_setprio(0); } while (0)
; #define PG8_WAIT_V(n) asm volatile("s_waitcnt vmcnt(" #n ")" ::: "memory")
; #define PG8_WAIT_L(n) asm volatile("s_waitcnt lgkmcnt(" #n ")" ::: "memory")
; #define PG8_BAR __builtin_amdgcn_s_barrier()
; #define PG8_SCHED __builtin_amdgcn_sched_barrier(0)
; template <class Epi, class Sched, bool ALIGN_EPI = false, bool SP2 = false>
; __device__ __forceinline__ void gemm_phase(PG8_LAS unsigned char* lds, const Gemm g, const Sched& S, const Epi& E) {
;     ...
;             PG8_LDB(B0, 1, 0); PG8_LDB(B1, 1, 1); PG8_SCHED; PG8_LDA(At, 1, 0); PG8_STAGE(PG8_SA(0, 1), a2 + hstepA, voffA);
;             PG8_WAIT_V(8); PG8_WAIT_L(0); PG8_BAR; PG8_MMA(0, 0, At, B0); PG8_MMA(0, 1, At, B1); PG8_BAR; PG8_SCHED;
	ds_read_b128 v[128:131], v240
	ds_read_b128 v[132:135], v240 offset:1024
	ds_read_b128 v[136:139], v240 offset:2048
	ds_read_b128 v[140:143], v240 offset:3072
	ds_read_b128 v[144:147], v241
	ds_read_b128 v[148:151], v241 offset:1024
	ds_read_b128 v[152:155], v241 offset:2048
	ds_read_b128 v[156:159], v241 offset:3072
	ds_read_b128 v[160:163], v225 offset:32768
	ds_read_b128 v[164:167], v225 offset:33792
	ds_read_b128 v[170:173], v225 offset:34816
	ds_read_b128 v[198:201], v225 offset:35840
	ds_read_b128 v[202:205], v225 offset:36864
	ds_read_b128 v[206:209], v225 offset:37888
	ds_read_b128 v[210:213], v225 offset:38912
	ds_read_b128 v[214:217], v225 offset:39936
	s_add_u32 s60, s60, 0x40000
	s_addc_u32 s61, s61, 0
	s_mov_b32 m0, s73
	v_lshl_add_u64 v[236:237], s[60:61], 0, v[192:193]
	global_load_lds_dwordx4 v[236:237], off
	v_lshl_add_u64 v[236:237], s[60:61], 0, v[190:191]
	s_mov_b32 m0, s80
	s_nop 0
	global_load_lds_dwordx4 v[236:237], off
	s_waitcnt vmcnt(8)
	s_waitcnt lgkmcnt(0)
	s_barrier
	s_setprio 1
	v_mfma_f32_16x16x32_bf16 v[124:127], v[128:131], v[160:163], v[124:127]
	v_mfma_f32_16x16x32_bf16 v[120:123], v[136:139], v[160:163], v[120:123]
	v_mfma_f32_16x16x32_bf16 v[108:111], v[128:131], v[170:173], v[108:111]
	v_mfma_f32_16x16x32_bf16 v[104:107], v[136:139], v[170:173], v[104:107]
	v_mfma_f32_16x16x32_bf16 v[92:95], v[128:131], v[202:205], v[92:95]
	v_mfma_f32_16x16x32_bf16 v[88:91], v[136:139], v[202:205], v[88:91]
	v_mfma_f32_16x16x32_bf16 v[76:79], v[128:131], v[210:213], v[76:79]
	v_mfma_f32_16x16x32_bf16 v[72:75], v[136:139], v[210:213], v[72:75]
	v_mfma_f32_16x16x32_bf16 v[124:127], v[132:135], v[164:167], v[124:127]
	v_mfma_f32_16x16x32_bf16 v[120:123], v[140:143], v[164:167], v[120:123]
	v_mfma_f32_16x16x32_bf16 v[108:111], v[132:135], v[198:201], v[108:111]
	v_mfma_f32_16x16x32_bf16 v[104:107], v[140:143], v[198:201], v[104:107]
	v_mfma_f32_16x16x32_bf16 v[92:95], v[132:135], v[206:209], v[92:95]
	v_mfma_f32_16x16x32_bf16 v[88:91], v[140:143], v[206:209], v[88:91]
	v_mfma_f32_16x16x32_bf16 v[76:79], v[132:135], v[214:217], v[76:79]
	v_mfma_f32_16x16x32_bf16 v[72:75], v[140:143], v[214:217], v[72:75]
	s_setprio 0
	s_setprio 1
	v_mfma_f32_16x16x32_bf16 v[116:119], v[144:147], v[160:163], v[116:119]
	v_mfma_f32_16x16x32_bf16 v[112:115], v[152:155], v[160:163], v[112:115]
	v_mfma_f32_16x16x32_bf16 v[100:103], v[144:147], v[170:173], v[100:103]
	v_mfma_f32_16x16x32_bf16 v[96:99], v[152:155], v[170:173], v[96:99]
	v_mfma_f32_16x16x32_bf16 v[84:87], v[144:147], v[202:205], v[84:87]
	v_mfma_f32_16x16x32_bf16 v[80:83], v[152:155], v[202:205], v[80:83]
	v_mfma_f32_16x16x32_bf16 v[68:71], v[144:147], v[210:213], v[68:71]
	v_mfma_f32_16x16x32_bf16 v[64:67], v[152:155], v[210:213], v[64:67]
	v_mfma_f32_16x16x32_bf16 v[116:119], v[148:151], v[164:167], v[116:119]
	v_mfma_f32_16x16x32_bf16 v[112:115], v[156:159], v[164:167], v[112:115]
	v_mfma_f32_16x16x32_bf16 v[100:103], v[148:151], v[198:201], v[100:103]
	v_mfma_f32_16x16x32_bf16 v[96:99], v[156:159], v[198:201], v[96:99]
	v_mfma_f32_16x16x32_bf16 v[84:87], v[148:151], v[206:209], v[84:87]
	s_add_i32 s60, s74, s34
	v_mfma_f32_16x16x32_bf16 v[80:83], v[156:159], v[206:209], v[80:83]
	v_lshl_add_u64 v[178:179], v[178:179], 0, s[30:31]
	v_mfma_f32_16x16x32_bf16 v[68:71], v[148:151], v[214:217], v[68:71]
	s_mov_b32 m0, s60
	v_mfma_f32_16x16x32_bf16 v[64:67], v[156:159], v[214:217], v[64:67]
	s_setprio 0
	s_barrier
; #define PG8_STAGE(bufoff, gbase, voff) do { _Pragma("unroll") for (int _i = 0; _i < 2; ++_i) \
;         __builtin_amdgcn_global_load_lds((const unsigned*)((const char*)(gbase) + (voff)[_i]), (PG8_LAS unsigned*)(lds + (bufoff) + ldsw + _i * 8192), 16, 0, 0); } while (0)
; #define PG8_LDA(dst, b, h) do { _Pragma("unroll") for (int m = 0; m < 4; ++m) _Pragma("unroll") for (int k = 0; k < 2; ++k) dst[m][k] = *(const PG8_LAS bf16x8*)(lds + PG8_SA(b, h) + aoff + m * 2048 + k * 1024); } while (0)
; #define PG8_LDB(dst, b, h) do { _Pragma("unroll") for (int n = 0; n < 2; ++n) _Pragma("unroll") for (int k = 0; k < 2; ++k) dst[n][k] = *(const PG8_LAS bf16x8*)(lds + PG8_SB(b, h) + boff + n * 2048 + k * 1024); } while (0)
; template <class Epi, class Sched, bool ALIGN_EPI = false, bool SP2 = false>
; __device__ __forceinline__ void gemm_phase(PG8_LAS unsigned char* lds, const Gemm g, const Sched& S, const Epi& E) {
;     ...
;         for (int t = 0; t < nt; t += 2) {
;             const bool last = (t == nt - 2);
;             const char* a1 = cA + (size_t)(t + 1) * kstepA;
;             const char* a2 = last ? nA : cA + (size_t)(t + 2) * kstepA; const char* b2 = last ? nB : cB + (size_t)(t + 2) * kstep;
;             const char* a3 = a2 + kstepA; const char* b3 = b2 + kstep;
;             if (last && has_next) S.a_ready(nxt);
;             if constexpr (SP2) {
;             PG8_LDB(B0, 0, 0); PG8_LDB(B1, 0, 1); PG8_SCHED; PG8_LDA(At, 0, 0); PG8_STAGE(PG8_SA(1, 1), a1 + hstepA, voffA);
;             PG8_WAIT_V(8); PG8_WAIT_L(0); PG8_BAR; PG8_MMA(0, 0, At, B0); PG8_MMA(0, 1, At, B1); PG8_BAR; PG8_SCHED;
;             PG8_LDA(At, 0, 1); PG8_STAGE(PG8_SB(0, 0), b2, voffB); PG8_STAGE(PG8_SB(0, 1), b2 + hstep, voffB); PG8_STAGE(PG8_SA(0, 0), a2, voffA);
;             PG8_WAIT_V(8); PG8_WAIT_L(0); PG8_BAR; PG8_MMA(1, 0, At, B0); PG8_MMA(1, 1, At, B1); PG8_BAR; PG8_SCHED;
;             PG8_LDB(B0, 1, 0); PG8_LDB(B1, 1, 1); PG8_SCHED; PG8_LDA(At, 1, 0); PG8_STAGE(PG8_SA(0, 1), a2 + hstepA, voffA);
;             PG8_WAIT_V(8); PG8_WAIT_L(0); PG8_BAR; PG8_MMA(0, 0, At, B0); PG8_MMA(0, 1, At, B1); PG8_BAR; PG8_SCHED;
;             PG8_LDA(At, 1, 1); PG8_STAGE(PG8_SB(1, 0), b3, voffB); PG8_STAGE(PG8_SB(1, 1), b3 + hstep, voffB); PG8_STAGE(PG8_SA(1, 0), a3, voffA);
;             PG8_WAIT_V(8); PG8_WAIT_L(0); PG8_BAR; PG8_MMA(1, 0, At, B0); PG8_MMA(1, 1, At, B1); PG8_BAR; PG8_SCHED;
	ds_read_b128 v[160:163], v225 offset:49152
	ds_read_b128 v[164:167], v225 offset:50176
	ds_read_b128 v[170:173], v225 offset:51200
	ds_read_b128 v[198:201], v225 offset:52224
	ds_read_b128 v[202:205], v225 offset:53248
	ds_read_b128 v[206:209], v225 offset:54272
	ds_read_b128 v[210:213], v225 offset:55296
	ds_read_b128 v[214:217], v225 offset:56320
	global_load_lds_dwordx4 v[178:179], off
	s_add_i32 m0, s60, 0x2000
	s_add_u32 s58, s58, 0x40080
	v_lshl_add_u64 v[178:179], v[218:219], 0, s[30:31]
	s_addc_u32 s59, s59, 0
	s_add_i32 s60, s75, s34
	global_load_lds_dwordx4 v[178:179], off
	v_lshl_add_u64 v[178:179], s[58:59], 0, v[168:169]
	s_mov_b32 m0, s60
	s_nop 0
	global_load_lds_dwordx4 v[178:179], off
	v_lshl_add_u64 v[178:179], s[58:59], 0, v[188:189]
	s_add_i32 m0, s60, 0x2000
	s_nop 0
	global_load_lds_dwordx4 v[178:179], off
	v_lshl_add_u64 v[178:179], v[220:221], 0, s[30:31]
	s_mov_b32 m0, s84
	s_nop 0
	global_load_lds_dwordx4 v[178:179], off
	v_lshl_add_u64 v[178:179], v[234:235], 0, s[30:31]
	s_mov_b32 m0, s85
	s_nop 0
	global_load_lds_dwordx4 v[178:179], off
	s_waitcnt vmcnt(8)
	s_waitcnt lgkmcnt(0)
	s_barrier
	s_setprio 1
	v_mfma_f32_16x16x32_bf16 v[60:63], v[128:131], v[160:163], v[60:63]
	v_mfma_f32_16x16x32_bf16 v[56:59], v[136:139], v[160:163], v[56:59]
	v_mfma_f32_16x16x32_bf16 v[44:47], v[128:131], v[170:173], v[44:47]
	v_mfma_f32_16x16x32_bf16 v[40:43], v[136:139], v[170:173], v[40:43]
	v_mfma_f32_16x16x32_bf16 v[28:31], v[128:131], v[202:205], v[28:31]
	v_mfma_f32_16x16x32_bf16 v[24:27], v[136:139], v[202:205], v[24:27]
	v_mfma_f32_16x16x32_bf16 v[12:15], v[128:131], v[210:213], v[12:15]
	v_mfma_f32_16x16x32_bf16 v[8:11], v[136:139], v[210:213], v[8:11]
	v_mfma_f32_16x16x32_bf16 v[60:63], v[132:135], v[164:167], v[60:63]
	v_mfma_f32_16x16x32_bf16 v[56:59], v[140:143], v[164:167], v[56:59]
	v_mfma_f32_16x16x32_bf16 v[44:47], v[132:135], v[198:201], v[44:47]
	v_mfma_f32_16x16x32_bf16 v[40:43], v[140:143], v[198:201], v[40:43]
	v_mfma_f32_16x16x32_bf16 v[28:31], v[132:135], v[206:209], v[28:31]
	v_mfma_f32_16x16x32_bf16 v[24:27], v[140:143], v[206:209], v[24:27]
	v_mfma_f32_16x16x32_bf16 v[12:15], v[132:135], v[214:217], v[12:15]
	v_mfma_f32_16x16x32_bf16 v[8:11], v[140:143], v[214:217], v[8:11]
	s_add_i32 s65, s65, 2
	s_setprio 0
	s_setprio 1
	v_mfma_f32_16x16x32_bf16 v[52:55], v[144:147], v[160:163], v[52:55]
	s_add_u32 s53, s53, 0x100
	v_mfma_f32_16x16x32_bf16 v[48:51], v[152:155], v[160:163], v[48:51]
	s_addc_u32 s64, s64, 0
	v_mfma_f32_16x16x32_bf16 v[36:39], v[144:147], v[170:173], v[36:39]
	s_add_u32 s40, s40, 0x100
	v_mfma_f32_16x16x32_bf16 v[32:35], v[152:155], v[170:173], v[32:35]
	s_addc_u32 s41, s41, 0
	v_mfma_f32_16x16x32_bf16 v[20:23], v[144:147], v[202:205], v[20:23]
	s_add_u32 s58, s40, 0xfffc0080
	v_mfma_f32_16x16x32_bf16 v[16:19], v[152:155], v[202:205], v[16:19]
	s_addc_u32 s59, s41, -1
	v_mfma_f32_16x16x32_bf16 v[4:7], v[144:147], v[210:213], v[4:7]
	s_add_i32 s74, 0, 0x10000
	v_mfma_f32_16x16x32_bf16 v[0:3], v[152:155], v[210:213], v[0:3]
	s_cmp_eq_u32 s65, 12
	v_mfma_f32_16x16x32_bf16 v[52:55], v[148:151], v[164:167], v[52:55]
	s_cselect_b32 s61, s5, s59
	v_mfma_f32_16x16x32_bf16 v[48:51], v[156:159], v[164:167], v[48:51]
	s_cselect_b32 s60, s6, s58
	v_mfma_f32_16x16x32_bf16 v[36:39], v[148:151], v[198:201], v[36:39]
	s_cselect_b32 s59, s7, s64
	v_mfma_f32_16x16x32_bf16 v[32:35], v[156:159], v[198:201], v[32:35]
	s_cselect_b32 s58, s51, s53
	v_mfma_f32_16x16x32_bf16 v[20:23], v[148:151], v[206:209], v[20:23]
	s_add_i32 s91, 0, 0x14000
	v_mfma_f32_16x16x32_bf16 v[16:19], v[156:159], v[206:209], v[16:19]
	v_add_u32_e32 v242, s74, v224
	v_mfma_f32_16x16x32_bf16 v[4:7], v[148:151], v[214:217], v[4:7]
	v_add_u32_e32 v243, s91, v224
	v_mfma_f32_16x16x32_bf16 v[0:3], v[156:159], v[214:217], v[0:3]
	s_setprio 0
	s_barrier
	.p2align	6

; #define PG8_STAGE(bufoff, gbase, voff) do { _Pragma("unroll") for (int _i = 0; _i < 2; ++_i) \
;         __builtin_amdgcn_global_load_lds((const unsigned*)((const char*)(gbase) + (voff)[_i]), (PG8_LAS unsigned*)(lds + (bufoff) + ldsw + _i * 8192), 16, 0, 0); } while (0)
; #define PG8_LDA(dst, b, h) do { _Pragma("unroll") for (int m = 0; m < 4; ++m) _Pragma("unroll") for (int k = 0; k < 2; ++k) dst[m][k] = *(const PG8_LAS bf16x8*)(lds + PG8_SA(b, h) + aoff + m * 2048 + k * 1024); } while (0)
; #define PG8_LDB(dst, b, h) do { _Pragma("unroll") for (int n = 0; n < 2; ++n) _Pragma("unroll") for (int k = 0; k < 2; ++k) dst[n][k] = *(const PG8_LAS bf16x8*)(lds + PG8_SB(b, h) + boff + n * 2048 + k * 1024); } while (0)
; #define PG8_WAIT_V(n) asm volatile("s_waitcnt vmcnt(" #n ")" ::: "memory")
; #define PG8_WAIT_L(n) asm volatile("s_waitcnt lgkmcnt(" #n ")" ::: "memory")
; #define PG8_BAR __builtin_amdgcn_s_barrier()
; #define PG8_SCHED __builtin_amdgcn_sched_barrier(0)
; template <class Epi, class Sched, bool ALIGN_EPI = false, bool SP2 = false>
; __device__ __forceinline__ void gemm_phase(PG8_LAS unsigned char* lds, const Gemm g, const Sched& S, const Epi& E) {
;     ...
;         const char* nA = has_next ? (const char*)g.A + (size_t)nxt.pm * tstepA : cA; const char* nB = has_next ? (const char*)g.Bt + (size_t)nxt.pn * tstep : cB;
;         for (int t = 0; t < nt; t += 2) {
;             const bool last = (t == nt - 2);
;             const char* a1 = cA + (size_t)(t + 1) * kstepA;
;             const char* a2 = last ? nA : cA + (size_t)(t + 2) * kstepA; const char* b2 = last ? nB : cB + (size_t)(t + 2) * kstep;
;             const char* a3 = a2 + kstepA; const char* b3 = b2 + kstep;
;             if (last && has_next) S.a_ready(nxt);
;             if constexpr (SP2) {
;             PG8_LDB(B0, 0, 0); PG8_LDB(B1, 0, 1); PG8_SCHED; PG8_LDA(At, 0, 0); PG8_STAGE(PG8_SA(1, 1), a1 + hstepA, voffA);
;             PG8_WAIT_V(8); PG8_WAIT_L(0); PG8_BAR; PG8_MMA(0, 0, At, B0); PG8_MMA(0, 1, At, B1); PG8_BAR; PG8_SCHED;
;             PG8_LDA(At, 0, 1); PG8_STAGE(PG8_SB(0, 0), b2, voffB); PG8_STAGE(PG8_SB(0, 1), b2 + hstep, voffB); PG8_STAGE(PG8_SA(0, 0), a2, voffA);
;             PG8_WAIT_V(8); PG8_WAIT_L(0); PG8_BAR; PG8_MMA(1, 0, At, B0); PG8_MMA(1, 1, At, B1); PG8_BAR; PG8_SCHED;
.LBB0_835:
	s_ashr_i32 s43, s42, 31
	s_lshl_b64 s[44:45], s[42:43], 19
	s_add_u32 s44, s20, s44
	s_addc_u32 s45, s21, s45
	s_and_b64 s[46:47], s[38:39], exec
	s_cselect_b32 s43, s45, s51
	s_cselect_b32 s61, s44, s50
	s_ashr_i32 s41, s40, 31
	s_lshl_b64 s[46:47], s[40:41], 19
	s_add_u32 s46, s2, s46
	s_addc_u32 s47, s3, s47
	s_and_b64 s[52:53], s[38:39], exec
	s_cselect_b32 s41, s47, s49
	s_cselect_b32 s64, s46, s48
	s_add_u32 s65, s48, 0x100
	s_addc_u32 s69, s49, 0
	s_add_u32 s48, s50, 0x40080
	s_addc_u32 s49, s51, 0
	s_mov_b32 s73, -2
	s_add_u32 s50, s48, 0xfffc0080
	s_addc_u32 s51, s49, -1
	s_add_i32 s74, 0, 0x10000
	s_cmp_eq_u32 s73, 12
	s_cselect_b32 s53, s43, s51
	s_cselect_b32 s52, s61, s50
	s_cselect_b32 s51, s41, s69
	s_cselect_b32 s50, s64, s65
	s_add_i32 s80, 0, 0x14000
	s_add_i32 m0, s7, 0xc000
	v_lshl_add_u64 v[178:179], s[48:49], 0, v[140:141]
	global_load_lds_dwordx4 v[178:179], off
	v_lshl_add_u64 v[178:179], s[48:49], 0, v[138:139]
	s_add_i32 m0, s7, 0xe000
	s_nop 0
	global_load_lds_dwordx4 v[178:179], off
	s_waitcnt vmcnt(8)
	s_waitcnt lgkmcnt(0)
	s_barrier
	s_setprio 1
	v_mfma_f32_16x16x32_bf16 v[124:127], v[144:147], v[192:195], 0
	v_mfma_f32_16x16x32_bf16 v[116:119], v[152:155], v[192:195], 0
	v_mfma_f32_16x16x32_bf16 v[108:111], v[144:147], v[200:203], 0
	v_mfma_f32_16x16x32_bf16 v[100:103], v[152:155], v[200:203], 0
	v_mfma_f32_16x16x32_bf16 v[92:95], v[144:147], v[208:211], 0
	v_mfma_f32_16x16x32_bf16 v[84:87], v[152:155], v[208:211], 0
	v_mfma_f32_16x16x32_bf16 v[76:79], v[144:147], v[216:219], 0
	v_mfma_f32_16x16x32_bf16 v[68:71], v[152:155], v[216:219], 0
	v_mfma_f32_16x16x32_bf16 v[124:127], v[148:151], v[196:199], v[124:127]
	v_mfma_f32_16x16x32_bf16 v[116:119], v[156:159], v[196:199], v[116:119]
	v_mfma_f32_16x16x32_bf16 v[108:111], v[148:151], v[204:207], v[108:111]
	v_mfma_f32_16x16x32_bf16 v[100:103], v[156:159], v[204:207], v[100:103]
	v_mfma_f32_16x16x32_bf16 v[92:95], v[148:151], v[212:215], v[92:95]
	v_mfma_f32_16x16x32_bf16 v[84:87], v[156:159], v[212:215], v[84:87]
	v_mfma_f32_16x16x32_bf16 v[76:79], v[148:151], v[220:223], v[76:79]
	v_mfma_f32_16x16x32_bf16 v[68:71], v[156:159], v[220:223], v[68:71]
	s_setprio 0
	s_setprio 1
	v_mfma_f32_16x16x32_bf16 v[120:123], v[160:163], v[192:195], 0
	v_mfma_f32_16x16x32_bf16 v[112:115], v[170:173], v[192:195], 0
	v_mfma_f32_16x16x32_bf16 v[104:107], v[160:163], v[200:203], 0
	v_mfma_f32_16x16x32_bf16 v[96:99], v[170:173], v[200:203], 0
	v_mfma_f32_16x16x32_bf16 v[88:91], v[160:163], v[208:211], 0
	v_mfma_f32_16x16x32_bf16 v[80:83], v[170:173], v[208:211], 0
	v_mfma_f32_16x16x32_bf16 v[72:75], v[160:163], v[216:219], 0
	v_mfma_f32_16x16x32_bf16 v[64:67], v[170:173], v[216:219], 0
	v_mfma_f32_16x16x32_bf16 v[120:123], v[164:167], v[196:199], v[120:123]
	v_mfma_f32_16x16x32_bf16 v[112:115], v[188:191], v[196:199], v[112:115]
	v_mfma_f32_16x16x32_bf16 v[104:107], v[164:167], v[204:207], v[104:107]
	v_mfma_f32_16x16x32_bf16 v[96:99], v[188:191], v[204:207], v[96:99]
	v_mfma_f32_16x16x32_bf16 v[88:91], v[164:167], v[212:215], v[88:91]
	s_add_i32 s74, s74, s6
	v_mfma_f32_16x16x32_bf16 v[80:83], v[188:191], v[212:215], v[80:83]
	v_lshl_add_u64 v[178:179], s[50:51], 0, v[132:133]
	v_mfma_f32_16x16x32_bf16 v[72:75], v[164:167], v[220:223], v[72:75]
	s_mov_b32 m0, s74
	v_mfma_f32_16x16x32_bf16 v[64:67], v[188:191], v[220:223], v[64:67]
	s_setprio 0
	s_barrier
	ds_read_b128 v[192:195], v143 offset:16384
	ds_read_b128 v[196:199], v143 offset:17408
	ds_read_b128 v[200:203], v143 offset:18432
	ds_read_b128 v[204:207], v143 offset:19456
	ds_read_b128 v[208:211], v143 offset:20480
	ds_read_b128 v[212:215], v143 offset:21504
	ds_read_b128 v[216:219], v143 offset:22528
	ds_read_b128 v[220:223], v143 offset:23552
	global_load_lds_dwordx4 v[178:179], off
	s_add_i32 m0, s74, 0x2000
	s_add_u32 s74, s50, 0x40000
	v_lshl_add_u64 v[224:225], s[50:51], 0, v[128:129]
	s_addc_u32 s75, s51, 0
	s_add_i32 s80, s80, s6
	global_load_lds_dwordx4 v[224:225], off
	v_lshl_add_u64 v[234:235], s[74:75], 0, v[132:133]
	s_mov_b32 m0, s80
	v_lshl_add_u64 v[236:237], s[52:53], 0, v[130:131]
	global_load_lds_dwordx4 v[234:235], off
	v_lshl_add_u64 v[234:235], s[74:75], 0, v[128:129]
	s_add_i32 m0, s80, 0x2000
	s_nop 0
	global_load_lds_dwordx4 v[234:235], off
	v_lshl_add_u64 v[234:235], s[52:53], 0, v[134:135]
	s_mov_b32 m0, s7
	s_nop 0
	global_load_lds_dwordx4 v[234:235], off
	s_mov_b32 m0, s34
	s_nop 0
	global_load_lds_dwordx4 v[236:237], off
	s_waitcnt vmcnt(8)
	s_waitcnt lgkmcnt(0)
	s_barrier
; #define PG8_STAGE(bufoff, gbase, voff) do { _Pragma("unroll") for (int _i = 0; _i < 2; ++_i) \
;         __builtin_amdgcn_global_load_lds((const unsigned*)((const char*)(gbase) + (voff)[_i]), (PG8_LAS unsigned*)(lds + (bufoff) + ldsw + _i * 8192), 16, 0, 0); } while (0)
; #define PG8_LDA(dst, b, h) do { _Pragma("unroll") for (int m = 0; m < 4; ++m) _Pragma("unroll") for (int k = 0; k < 2; ++k) dst[m][k] = *(const PG8_LAS bf16x8*)(lds + PG8_SA(b, h) + aoff + m * 2048 + k * 1024); } while (0)
; #define PG8_LDB(dst, b, h) do { _Pragma("unroll") for (int n = 0; n < 2; ++n) _Pragma("unroll") for (int k = 0; k < 2; ++k) dst[n][k] = *(const PG8_LAS bf16x8*)(lds + PG8_SB(b, h) + boff + n * 2048 + k * 1024); } while (0)
; #define PG8_MMA(ai, bj, At, Bt) do { __builtin_amdgcn_s_setprio(1); _Pragma("unroll") for (int m = 0; m < 4; ++m) _Pragma("unroll") for (int n = 0; n < 2; ++n) _Pragma("unroll") for (int k = 0; k < 2; ++k) \
;         acc[ai][bj][m][n] = __builtin_amdgcn_mfma_f32_16x16x32_bf16(Bt[n][k], At[m][k], acc[ai][bj][m][n], 0, 0, 0); __builtin_amdgcn_s_setprio(0); } while (0)
; #define PG8_WAIT_V(n) asm volatile("s_waitcnt vmcnt(" #n ")" ::: "memory")
; #define PG8_WAIT_L(n) asm volatile("s_waitcnt lgkmcnt(" #n ")" ::: "memory")
; #define PG8_BAR __builtin_amdgcn_s_barrier()
; #define PG8_SCHED __builtin_amdgcn_sched_barrier(0)
; template <class Epi, class Sched, bool ALIGN_EPI = false, bool SP2 = false>
; __device__ __forceinline__ void gemm_phase(PG8_LAS unsigned char* lds, const Gemm g, const Sched& S, const Epi& E) {
;     ...
;             PG8_WAIT_V(8); PG8_WAIT_L(0); PG8_BAR; PG8_MMA(1, 0, At, B0); PG8_MMA(1, 1, At, B1); PG8_BAR; PG8_SCHED;
;             PG8_LDB(B0, 1, 0); PG8_LDB(B1, 1, 1); PG8_SCHED; PG8_LDA(At, 1, 0); PG8_STAGE(PG8_SA(0, 1), a2 + hstepA, voffA);
;             PG8_WAIT_V(8); PG8_WAIT_L(0); PG8_BAR; PG8_MMA(0, 0, At, B0); PG8_MMA(0, 1, At, B1); PG8_BAR; PG8_SCHED;
	s_setprio 1
	v_mfma_f32_16x16x32_bf16 v[60:63], v[144:147], v[192:195], 0
	v_mfma_f32_16x16x32_bf16 v[52:55], v[152:155], v[192:195], 0
	v_mfma_f32_16x16x32_bf16 v[44:47], v[144:147], v[200:203], 0
	v_mfma_f32_16x16x32_bf16 v[36:39], v[152:155], v[200:203], 0
	v_mfma_f32_16x16x32_bf16 v[28:31], v[144:147], v[208:211], 0
	v_mfma_f32_16x16x32_bf16 v[20:23], v[152:155], v[208:211], 0
	v_mfma_f32_16x16x32_bf16 v[12:15], v[144:147], v[216:219], 0
	v_mfma_f32_16x16x32_bf16 v[4:7], v[152:155], v[216:219], 0
	v_mfma_f32_16x16x32_bf16 v[60:63], v[148:151], v[196:199], v[60:63]
	v_mfma_f32_16x16x32_bf16 v[52:55], v[156:159], v[196:199], v[52:55]
	v_mfma_f32_16x16x32_bf16 v[44:47], v[148:151], v[204:207], v[44:47]
	v_mfma_f32_16x16x32_bf16 v[36:39], v[156:159], v[204:207], v[36:39]
	v_mfma_f32_16x16x32_bf16 v[28:31], v[148:151], v[212:215], v[28:31]
	v_mfma_f32_16x16x32_bf16 v[20:23], v[156:159], v[212:215], v[20:23]
	v_mfma_f32_16x16x32_bf16 v[12:15], v[148:151], v[220:223], v[12:15]
	v_mfma_f32_16x16x32_bf16 v[4:7], v[156:159], v[220:223], v[4:7]
	s_setprio 0
	s_setprio 1
	v_mfma_f32_16x16x32_bf16 v[56:59], v[160:163], v[192:195], 0
	v_mfma_f32_16x16x32_bf16 v[48:51], v[170:173], v[192:195], 0
	v_mfma_f32_16x16x32_bf16 v[40:43], v[160:163], v[200:203], 0
	v_mfma_f32_16x16x32_bf16 v[32:35], v[170:173], v[200:203], 0
	v_mfma_f32_16x16x32_bf16 v[24:27], v[160:163], v[208:211], 0
	v_mfma_f32_16x16x32_bf16 v[16:19], v[170:173], v[208:211], 0
	v_mfma_f32_16x16x32_bf16 v[8:11], v[160:163], v[216:219], 0
	v_mfma_f32_16x16x32_bf16 v[0:3], v[170:173], v[216:219], 0
	v_mfma_f32_16x16x32_bf16 v[56:59], v[164:167], v[196:199], v[56:59]
	v_mfma_f32_16x16x32_bf16 v[48:51], v[188:191], v[196:199], v[48:51]
	v_mfma_f32_16x16x32_bf16 v[40:43], v[164:167], v[204:207], v[40:43]
	v_mfma_f32_16x16x32_bf16 v[32:35], v[188:191], v[204:207], v[32:35]
	s_add_i32 s74, 0, 0x18000
	v_mfma_f32_16x16x32_bf16 v[24:27], v[164:167], v[212:215], v[24:27]
	s_add_i32 s75, 0, 0x1c000
	v_mfma_f32_16x16x32_bf16 v[16:19], v[188:191], v[212:215], v[16:19]
	v_add_u32_e32 v240, s74, v142
	v_mfma_f32_16x16x32_bf16 v[8:11], v[164:167], v[220:223], v[8:11]
	v_add_u32_e32 v241, s75, v142
	v_mfma_f32_16x16x32_bf16 v[0:3], v[188:191], v[220:223], v[0:3]
	s_setprio 0
	s_barrier
	ds_read_b128 v[144:147], v240
	ds_read_b128 v[148:151], v240 offset:1024
	ds_read_b128 v[152:155], v240 offset:2048
	ds_read_b128 v[156:159], v240 offset:3072
	ds_read_b128 v[160:163], v241
	ds_read_b128 v[164:167], v241 offset:1024
	ds_read_b128 v[170:173], v241 offset:2048
	ds_read_b128 v[188:191], v241 offset:3072
	ds_read_b128 v[192:195], v143 offset:32768
	ds_read_b128 v[196:199], v143 offset:33792
	ds_read_b128 v[200:203], v143 offset:34816
	ds_read_b128 v[204:207], v143 offset:35840
	ds_read_b128 v[208:211], v143 offset:36864
	ds_read_b128 v[212:215], v143 offset:37888
	ds_read_b128 v[216:219], v143 offset:38912
	ds_read_b128 v[220:223], v143 offset:39936
	s_add_u32 s52, s52, 0x40000
	s_addc_u32 s53, s53, 0
	s_mov_b32 m0, s35
	v_lshl_add_u64 v[238:239], s[52:53], 0, v[134:135]
	global_load_lds_dwordx4 v[238:239], off
	v_lshl_add_u64 v[238:239], s[52:53], 0, v[130:131]
	s_mov_b32 m0, s54
	s_nop 0
	global_load_lds_dwordx4 v[238:239], off
	s_waitcnt vmcnt(8)
	s_waitcnt lgkmcnt(0)
	s_barrier
	s_setprio 1
	v_mfma_f32_16x16x32_bf16 v[124:127], v[144:147], v[192:195], v[124:127]
	v_mfma_f32_16x16x32_bf16 v[116:119], v[152:155], v[192:195], v[116:119]
	v_mfma_f32_16x16x32_bf16 v[108:111], v[144:147], v[200:203], v[108:111]
	v_mfma_f32_16x16x32_bf16 v[100:103], v[152:155], v[200:203], v[100:103]
	v_mfma_f32_16x16x32_bf16 v[92:95], v[144:147], v[208:211], v[92:95]
	v_mfma_f32_16x16x32_bf16 v[84:87], v[152:155], v[208:211], v[84:87]
	v_mfma_f32_16x16x32_bf16 v[76:79], v[144:147], v[216:219], v[76:79]
	v_mfma_f32_16x16x32_bf16 v[68:71], v[152:155], v[216:219], v[68:71]
	v_mfma_f32_16x16x32_bf16 v[124:127], v[148:151], v[196:199], v[124:127]
	v_mfma_f32_16x16x32_bf16 v[116:119], v[156:159], v[196:199], v[116:119]
	v_mfma_f32_16x16x32_bf16 v[108:111], v[148:151], v[204:207], v[108:111]
	v_mfma_f32_16x16x32_bf16 v[100:103], v[156:159], v[204:207], v[100:103]
	v_mfma_f32_16x16x32_bf16 v[92:95], v[148:151], v[212:215], v[92:95]
	v_mfma_f32_16x16x32_bf16 v[84:87], v[156:159], v[212:215], v[84:87]
	v_mfma_f32_16x16x32_bf16 v[76:79], v[148:151], v[220:223], v[76:79]
	v_mfma_f32_16x16x32_bf16 v[68:71], v[156:159], v[220:223], v[68:71]
	s_setprio 0
	s_setprio 1
	v_mfma_f32_16x16x32_bf16 v[120:123], v[160:163], v[192:195], v[120:123]
	v_mfma_f32_16x16x32_bf16 v[112:115], v[170:173], v[192:195], v[112:115]
	v_mfma_f32_16x16x32_bf16 v[104:107], v[160:163], v[200:203], v[104:107]
	v_mfma_f32_16x16x32_bf16 v[96:99], v[170:173], v[200:203], v[96:99]
	v_mfma_f32_16x16x32_bf16 v[88:91], v[160:163], v[208:211], v[88:91]
	v_mfma_f32_16x16x32_bf16 v[80:83], v[170:173], v[208:211], v[80:83]
	v_mfma_f32_16x16x32_bf16 v[72:75], v[160:163], v[216:219], v[72:75]
	v_mfma_f32_16x16x32_bf16 v[64:67], v[170:173], v[216:219], v[64:67]
	v_mfma_f32_16x16x32_bf16 v[120:123], v[164:167], v[196:199], v[120:123]
	v_mfma_f32_16x16x32_bf16 v[112:115], v[188:191], v[196:199], v[112:115]
	v_mfma_f32_16x16x32_bf16 v[104:107], v[164:167], v[204:207], v[104:107]
	v_mfma_f32_16x16x32_bf16 v[96:99], v[188:191], v[204:207], v[96:99]
	v_mfma_f32_16x16x32_bf16 v[88:91], v[164:167], v[212:215], v[88:91]
	s_add_i32 s52, s74, s6
	v_mfma_f32_16x16x32_bf16 v[80:83], v[188:191], v[212:215], v[80:83]
	v_lshl_add_u64 v[178:179], v[178:179], 0, s[30:31]
	v_mfma_f32_16x16x32_bf16 v[72:75], v[164:167], v[220:223], v[72:75]
	s_mov_b32 m0, s52
	v_mfma_f32_16x16x32_bf16 v[64:67], v[188:191], v[220:223], v[64:67]
	s_setprio 0
	s_barrier
; #define PG8_STAGE(bufoff, gbase, voff) do { _Pragma("unroll") for (int _i = 0; _i < 2; ++_i) \
;         __builtin_amdgcn_global_load_lds((const unsigned*)((const char*)(gbase) + (voff)[_i]), (PG8_LAS unsigned*)(lds + (bufoff) + ldsw + _i * 8192), 16, 0, 0); } while (0)
; #define PG8_LDA(dst, b, h) do { _Pragma("unroll") for (int m = 0; m < 4; ++m) _Pragma("unroll") for (int k = 0; k < 2; ++k) dst[m][k] = *(const PG8_LAS bf16x8*)(lds + PG8_SA(b, h) + aoff + m * 2048 + k * 1024); } while (0)
; #define PG8_LDB(dst, b, h) do { _Pragma("unroll") for (int n = 0; n < 2; ++n) _Pragma("unroll") for (int k = 0; k < 2; ++k) dst[n][k] = *(const PG8_LAS bf16x8*)(lds + PG8_SB(b, h) + boff + n * 2048 + k * 1024); } while (0)
; template <class Epi, class Sched, bool ALIGN_EPI = false, bool SP2 = false>
; __device__ __forceinline__ void gemm_phase(PG8_LAS unsigned char* lds, const Gemm g, const Sched& S, const Epi& E) {
;     ...
;         for (int t = 0; t < nt; t += 2) {
;             const bool last = (t == nt - 2);
;             const char* a1 = cA + (size_t)(t + 1) * kstepA;
;             const char* a2 = last ? nA : cA + (size_t)(t + 2) * kstepA; const char* b2 = last ? nB : cB + (size_t)(t + 2) * kstep;
;             const char* a3 = a2 + kstepA; const char* b3 = b2 + kstep;
;             if (last && has_next) S.a_ready(nxt);
;             if constexpr (SP2) {
;             PG8_LDB(B0, 0, 0); PG8_LDB(B1, 0, 1); PG8_SCHED; PG8_LDA(At, 0, 0); PG8_STAGE(PG8_SA(1, 1), a1 + hstepA, voffA);
;             PG8_WAIT_V(8); PG8_WAIT_L(0); PG8_BAR; PG8_MMA(0, 0, At, B0); PG8_MMA(0, 1, At, B1); PG8_BAR; PG8_SCHED;
;             PG8_LDA(At, 0, 1); PG8_STAGE(PG8_SB(0, 0), b2, voffB); PG8_STAGE(PG8_SB(0, 1), b2 + hstep, voffB); PG8_STAGE(PG8_SA(0, 0), a2, voffA);
;             PG8_WAIT_V(8); PG8_WAIT_L(0); PG8_BAR; PG8_MMA(1, 0, At, B0); PG8_MMA(1, 1, At, B1); PG8_BAR; PG8_SCHED;
;             PG8_LDB(B0, 1, 0); PG8_LDB(B1, 1, 1); PG8_SCHED; PG8_LDA(At, 1, 0); PG8_STAGE(PG8_SA(0, 1), a2 + hstepA, voffA);
;             PG8_WAIT_V(8); PG8_WAIT_L(0); PG8_BAR; PG8_MMA(0, 0, At, B0); PG8_MMA(0, 1, At, B1); PG8_BAR; PG8_SCHED;
;             PG8_LDA(At, 1, 1); PG8_STAGE(PG8_SB(1, 0), b3, voffB); PG8_STAGE(PG8_SB(1, 1), b3 + hstep, voffB); PG8_STAGE(PG8_SA(1, 0), a3, voffA);
;             PG8_WAIT_V(8); PG8_WAIT_L(0); PG8_BAR; PG8_MMA(1, 0, At, B0); PG8_MMA(1, 1, At, B1); PG8_BAR; PG8_SCHED;
	ds_read_b128 v[192:195], v143 offset:49152
	ds_read_b128 v[196:199], v143 offset:50176
	ds_read_b128 v[200:203], v143 offset:51200
	ds_read_b128 v[204:207], v143 offset:52224
	ds_read_b128 v[208:211], v143 offset:53248
	ds_read_b128 v[212:215], v143 offset:54272
	ds_read_b128 v[216:219], v143 offset:55296
	ds_read_b128 v[220:223], v143 offset:56320
	global_load_lds_dwordx4 v[178:179], off
	s_add_i32 m0, s52, 0x2000
	s_add_u32 s50, s50, 0x40080
	v_lshl_add_u64 v[178:179], v[224:225], 0, s[30:31]
	s_addc_u32 s51, s51, 0
	s_add_i32 s52, s75, s6
	global_load_lds_dwordx4 v[178:179], off
	v_lshl_add_u64 v[178:179], s[50:51], 0, v[132:133]
	s_mov_b32 m0, s52
	s_nop 0
	global_load_lds_dwordx4 v[178:179], off
	v_lshl_add_u64 v[178:179], s[50:51], 0, v[128:129]
	s_add_i32 m0, s52, 0x2000
	s_nop 0
	global_load_lds_dwordx4 v[178:179], off
	v_lshl_add_u64 v[178:179], v[234:235], 0, s[30:31]
	s_mov_b32 m0, s55
	s_nop 0
	global_load_lds_dwordx4 v[178:179], off
	v_lshl_add_u64 v[178:179], v[236:237], 0, s[30:31]
	s_mov_b32 m0, s56
	s_nop 0
	global_load_lds_dwordx4 v[178:179], off
	s_waitcnt vmcnt(8)
	s_waitcnt lgkmcnt(0)
	s_barrier
	s_setprio 1
	v_mfma_f32_16x16x32_bf16 v[60:63], v[144:147], v[192:195], v[60:63]
	v_mfma_f32_16x16x32_bf16 v[52:55], v[152:155], v[192:195], v[52:55]
	v_mfma_f32_16x16x32_bf16 v[44:47], v[144:147], v[200:203], v[44:47]
	v_mfma_f32_16x16x32_bf16 v[36:39], v[152:155], v[200:203], v[36:39]
	v_mfma_f32_16x16x32_bf16 v[28:31], v[144:147], v[208:211], v[28:31]
	v_mfma_f32_16x16x32_bf16 v[20:23], v[152:155], v[208:211], v[20:23]
	v_mfma_f32_16x16x32_bf16 v[12:15], v[144:147], v[216:219], v[12:15]
	v_mfma_f32_16x16x32_bf16 v[4:7], v[152:155], v[216:219], v[4:7]
	v_mfma_f32_16x16x32_bf16 v[60:63], v[148:151], v[196:199], v[60:63]
	v_mfma_f32_16x16x32_bf16 v[52:55], v[156:159], v[196:199], v[52:55]
	v_mfma_f32_16x16x32_bf16 v[44:47], v[148:151], v[204:207], v[44:47]
	v_mfma_f32_16x16x32_bf16 v[36:39], v[156:159], v[204:207], v[36:39]
	v_mfma_f32_16x16x32_bf16 v[28:31], v[148:151], v[212:215], v[28:31]
	v_mfma_f32_16x16x32_bf16 v[20:23], v[156:159], v[212:215], v[20:23]
	v_mfma_f32_16x16x32_bf16 v[12:15], v[148:151], v[220:223], v[12:15]
	v_mfma_f32_16x16x32_bf16 v[4:7], v[156:159], v[220:223], v[4:7]
	s_add_i32 s73, s73, 2
	s_setprio 0
	s_setprio 1
	v_mfma_f32_16x16x32_bf16 v[56:59], v[160:163], v[192:195], v[56:59]
	s_add_u32 s65, s65, 0x100
	v_mfma_f32_16x16x32_bf16 v[48:51], v[170:173], v[192:195], v[48:51]
	s_addc_u32 s69, s69, 0
	v_mfma_f32_16x16x32_bf16 v[40:43], v[160:163], v[200:203], v[40:43]
	s_add_u32 s48, s48, 0x100
	v_mfma_f32_16x16x32_bf16 v[32:35], v[170:173], v[200:203], v[32:35]
	s_addc_u32 s49, s49, 0
	v_mfma_f32_16x16x32_bf16 v[24:27], v[160:163], v[208:211], v[24:27]
	s_add_u32 s50, s48, 0xfffc0080
	v_mfma_f32_16x16x32_bf16 v[16:19], v[170:173], v[208:211], v[16:19]
	s_addc_u32 s51, s49, -1
	v_mfma_f32_16x16x32_bf16 v[8:11], v[160:163], v[216:219], v[8:11]
	s_add_i32 s74, 0, 0x10000
	v_mfma_f32_16x16x32_bf16 v[0:3], v[170:173], v[216:219], v[0:3]
	s_cmp_eq_u32 s73, 12
	v_mfma_f32_16x16x32_bf16 v[56:59], v[164:167], v[196:199], v[56:59]
	s_cselect_b32 s53, s43, s51
	v_mfma_f32_16x16x32_bf16 v[48:51], v[188:191], v[196:199], v[48:51]
	s_cselect_b32 s52, s61, s50
	v_mfma_f32_16x16x32_bf16 v[40:43], v[164:167], v[204:207], v[40:43]
	s_cselect_b32 s51, s41, s69
	v_mfma_f32_16x16x32_bf16 v[32:35], v[188:191], v[204:207], v[32:35]
	s_cselect_b32 s50, s64, s65
	v_mfma_f32_16x16x32_bf16 v[24:27], v[164:167], v[212:215], v[24:27]
	s_add_i32 s80, 0, 0x14000
	v_mfma_f32_16x16x32_bf16 v[16:19], v[188:191], v[212:215], v[16:19]
	v_add_u32_e32 v242, s74, v142
	v_mfma_f32_16x16x32_bf16 v[8:11], v[164:167], v[220:223], v[8:11]
	v_add_u32_e32 v178, s80, v142
	v_mfma_f32_16x16x32_bf16 v[0:3], v[188:191], v[220:223], v[0:3]
	s_setprio 0
	s_barrier
	.p2align	6

; #define PG8_STAGE(bufoff, gbase, voff) do { _Pragma("unroll") for (int _i = 0; _i < 2; ++_i) \
;         __builtin_amdgcn_global_load_lds((const unsigned*)((const char*)(gbase) + (voff)[_i]), (PG8_LAS unsigned*)(lds + (bufoff) + ldsw + _i * 8192), 16, 0, 0); } while (0)
; #define PG8_LDA(dst, b, h) do { _Pragma("unroll") for (int m = 0; m < 4; ++m) _Pragma("unroll") for (int k = 0; k < 2; ++k) dst[m][k] = *(const PG8_LAS bf16x8*)(lds + PG8_SA(b, h) + aoff + m * 2048 + k * 1024); } while (0)
; #define PG8_BAR __builtin_amdgcn_s_barrier()
; template <class Epi, class Sched, bool ALIGN_EPI = false, bool SP2 = false>
; __device__ __forceinline__ void gemm_phase(PG8_LAS unsigned char* lds, const Gemm g, const Sched& S, const Epi& E) {
;     ...
;         const char* nA = has_next ? (const char*)g.A + (size_t)nxt.pm * tstepA : cA; const char* nB = has_next ? (const char*)g.Bt + (size_t)nxt.pn * tstep : cB;
;         for (int t = 0; t < nt; t += 2) {
;             const bool last = (t == nt - 2);
;             const char* a1 = cA + (size_t)(t + 1) * kstepA;
;             const char* a2 = last ? nA : cA + (size_t)(t + 2) * kstepA; const char* b2 = last ? nB : cB + (size_t)(t + 2) * kstep;
;             const char* a3 = a2 + kstepA; const char* b3 = b2 + kstep;
;             if (last && has_next) S.a_ready(nxt);
;             if constexpr (SP2) {
;             PG8_LDB(B0, 0, 0); PG8_LDB(B1, 0, 1); PG8_SCHED; PG8_LDA(At, 0, 0); PG8_STAGE(PG8_SA(1, 1), a1 + hstepA, voffA);
;             PG8_WAIT_V(8); PG8_WAIT_L(0); PG8_BAR; PG8_MMA(0, 0, At, B0); PG8_MMA(0, 1, At, B1); PG8_BAR; PG8_SCHED;
;             PG8_LDA(At, 0, 1); PG8_STAGE(PG8_SB(0, 0), b2, voffB); PG8_STAGE(PG8_SB(0, 1), b2 + hstep, voffB); PG8_STAGE(PG8_SA(0, 0), a2, voffA);
;             PG8_WAIT_V(8); PG8_WAIT_L(0); PG8_BAR; PG8_MMA(1, 0, At, B0); PG8_MMA(1, 1, At, B1); PG8_BAR; PG8_SCHED;
;             PG8_LDB(B0, 1, 0); PG8_LDB(B1, 1, 1); PG8_SCHED; PG8_LDA(At, 1, 0); PG8_STAGE(PG8_SA(0, 1), a2 + hstepA, voffA);
;             PG8_WAIT_V(8); PG8_WAIT_L(0); PG8_BAR; PG8_MMA(0, 0, At, B0); PG8_MMA(0, 1, At, B1); PG8_BAR; PG8_SCHED;
;             PG8_LDA(At, 1, 1); PG8_STAGE(PG8_SB(1, 0), b3, voffB); PG8_STAGE(PG8_SB(1, 1), b3 + hstep, voffB); PG8_STAGE(PG8_SA(1, 0), a3, voffA);
;             PG8_WAIT_V(8); PG8_WAIT_L(0); PG8_BAR; PG8_MMA(1, 0, At, B0); PG8_MMA(1, 1, At, B1); PG8_BAR; PG8_SCHED;
.LBB0_912:
	s_add_u32 s5, s52, 0x100
	s_addc_u32 s6, s53, 0
	s_add_u32 s40, s54, 0xb4000
	s_addc_u32 s41, s55, 0
	s_mov_b32 s7, -2
	s_add_u32 s52, s40, 0xfff54000
	s_addc_u32 s53, s41, -1
	s_cmp_eq_u32 s7, 40
	s_cselect_b32 s56, s48, s52
	s_cselect_b32 s57, s49, s53
	s_cselect_b32 s54, s50, s5
	s_cselect_b32 s55, s51, s6
	s_add_u32 s52, s56, 0x4000
	s_addc_u32 s53, s57, 0
	s_add_i32 s64, 0, 0x10000
	s_add_i32 s74, 0, 0x14000
	s_add_i32 m0, s3, 0xc000
	v_lshl_add_u64 v[178:179], s[40:41], 0, v[196:197]
	global_load_lds_dwordx4 v[178:179], off
	v_lshl_add_u64 v[178:179], s[40:41], 0, v[194:195]
	s_add_i32 m0, s3, 0xe000
	s_nop 0
	global_load_lds_dwordx4 v[178:179], off
	s_waitcnt vmcnt(8)
	s_waitcnt lgkmcnt(0)
	s_barrier
	s_setprio 1
	v_mfma_f32_16x16x32_bf16 v[124:127], v[128:131], v[160:163], 0
	v_mfma_f32_16x16x32_bf16 v[120:123], v[136:139], v[160:163], 0
	v_mfma_f32_16x16x32_bf16 v[108:111], v[128:131], v[170:173], 0
	v_mfma_f32_16x16x32_bf16 v[104:107], v[136:139], v[170:173], 0
	v_mfma_f32_16x16x32_bf16 v[92:95], v[128:131], v[202:205], 0
	v_mfma_f32_16x16x32_bf16 v[88:91], v[136:139], v[202:205], 0
	v_mfma_f32_16x16x32_bf16 v[76:79], v[128:131], v[210:213], 0
	v_mfma_f32_16x16x32_bf16 v[72:75], v[136:139], v[210:213], 0
	v_mfma_f32_16x16x32_bf16 v[124:127], v[132:135], v[164:167], v[124:127]
	v_mfma_f32_16x16x32_bf16 v[120:123], v[140:143], v[164:167], v[120:123]
	v_mfma_f32_16x16x32_bf16 v[108:111], v[132:135], v[198:201], v[108:111]
	v_mfma_f32_16x16x32_bf16 v[104:107], v[140:143], v[198:201], v[104:107]
	v_mfma_f32_16x16x32_bf16 v[92:95], v[132:135], v[206:209], v[92:95]
	v_mfma_f32_16x16x32_bf16 v[88:91], v[140:143], v[206:209], v[88:91]
	v_mfma_f32_16x16x32_bf16 v[76:79], v[132:135], v[214:217], v[76:79]
	v_mfma_f32_16x16x32_bf16 v[72:75], v[140:143], v[214:217], v[72:75]
	s_setprio 0
	s_setprio 1
	v_mfma_f32_16x16x32_bf16 v[116:119], v[144:147], v[160:163], 0
	v_mfma_f32_16x16x32_bf16 v[112:115], v[152:155], v[160:163], 0
	v_mfma_f32_16x16x32_bf16 v[100:103], v[144:147], v[170:173], 0
	v_mfma_f32_16x16x32_bf16 v[96:99], v[152:155], v[170:173], 0
	v_mfma_f32_16x16x32_bf16 v[84:87], v[144:147], v[202:205], 0
	v_mfma_f32_16x16x32_bf16 v[80:83], v[152:155], v[202:205], 0
	v_mfma_f32_16x16x32_bf16 v[68:71], v[144:147], v[210:213], 0
	v_mfma_f32_16x16x32_bf16 v[64:67], v[152:155], v[210:213], 0
	v_mfma_f32_16x16x32_bf16 v[116:119], v[148:151], v[164:167], v[116:119]
	v_mfma_f32_16x16x32_bf16 v[112:115], v[156:159], v[164:167], v[112:115]
	v_mfma_f32_16x16x32_bf16 v[100:103], v[148:151], v[198:201], v[100:103]
	v_mfma_f32_16x16x32_bf16 v[96:99], v[156:159], v[198:201], v[96:99]
	v_mfma_f32_16x16x32_bf16 v[84:87], v[148:151], v[206:209], v[84:87]
	s_add_i32 s64, s64, s2
	v_mfma_f32_16x16x32_bf16 v[80:83], v[156:159], v[206:209], v[80:83]
	v_lshl_add_u64 v[178:179], s[54:55], 0, v[168:169]
	v_mfma_f32_16x16x32_bf16 v[68:71], v[148:151], v[214:217], v[68:71]
	s_mov_b32 m0, s64
	v_mfma_f32_16x16x32_bf16 v[64:67], v[156:159], v[214:217], v[64:67]
	s_setprio 0
	s_barrier
	ds_read_b128 v[160:163], v225 offset:16384
	ds_read_b128 v[164:167], v225 offset:17408
	ds_read_b128 v[170:173], v225 offset:18432
	ds_read_b128 v[198:201], v225 offset:19456
	ds_read_b128 v[202:205], v225 offset:20480
	ds_read_b128 v[206:209], v225 offset:21504
	ds_read_b128 v[210:213], v225 offset:22528
	ds_read_b128 v[214:217], v225 offset:23552
	global_load_lds_dwordx4 v[178:179], off
	s_add_i32 m0, s64, 0x2000
	s_add_u32 s64, s54, 0xb0000
	v_lshl_add_u64 v[218:219], s[54:55], 0, v[188:189]
	s_addc_u32 s65, s55, 0
	s_add_i32 s74, s74, s2
	global_load_lds_dwordx4 v[218:219], off
	v_lshl_add_u64 v[220:221], s[64:65], 0, v[168:169]
	s_mov_b32 m0, s74
	s_nop 0
	global_load_lds_dwordx4 v[220:221], off
	v_lshl_add_u64 v[220:221], s[64:65], 0, v[188:189]
	s_add_i32 m0, s74, 0x2000
	s_nop 0
	global_load_lds_dwordx4 v[220:221], off
	v_lshl_add_u64 v[220:221], s[56:57], 0, v[192:193]
	s_mov_b32 m0, s3
	s_nop 0
	global_load_lds_dwordx4 v[220:221], off
	v_lshl_add_u64 v[220:221], s[56:57], 0, v[190:191]
	s_mov_b32 m0, s34
	s_nop 0
	global_load_lds_dwordx4 v[220:221], off
	s_waitcnt vmcnt(8)
	s_waitcnt lgkmcnt(0)
	s_barrier
	s_setprio 1
	v_mfma_f32_16x16x32_bf16 v[60:63], v[128:131], v[160:163], 0
	v_mfma_f32_16x16x32_bf16 v[56:59], v[136:139], v[160:163], 0
	v_mfma_f32_16x16x32_bf16 v[44:47], v[128:131], v[170:173], 0
	v_mfma_f32_16x16x32_bf16 v[40:43], v[136:139], v[170:173], 0
	v_mfma_f32_16x16x32_bf16 v[28:31], v[128:131], v[202:205], 0
	v_mfma_f32_16x16x32_bf16 v[24:27], v[136:139], v[202:205], 0
	v_mfma_f32_16x16x32_bf16 v[12:15], v[128:131], v[210:213], 0
	v_mfma_f32_16x16x32_bf16 v[8:11], v[136:139], v[210:213], 0
	v_mfma_f32_16x16x32_bf16 v[60:63], v[132:135], v[164:167], v[60:63]
	v_mfma_f32_16x16x32_bf16 v[56:59], v[140:143], v[164:167], v[56:59]
	v_mfma_f32_16x16x32_bf16 v[44:47], v[132:135], v[198:201], v[44:47]
	v_mfma_f32_16x16x32_bf16 v[40:43], v[140:143], v[198:201], v[40:43]
	v_mfma_f32_16x16x32_bf16 v[28:31], v[132:135], v[206:209], v[28:31]
	v_mfma_f32_16x16x32_bf16 v[24:27], v[140:143], v[206:209], v[24:27]
	v_mfma_f32_16x16x32_bf16 v[12:15], v[132:135], v[214:217], v[12:15]
	v_mfma_f32_16x16x32_bf16 v[8:11], v[140:143], v[214:217], v[8:11]
	s_setprio 0
	s_setprio 1
	v_mfma_f32_16x16x32_bf16 v[52:55], v[144:147], v[160:163], 0
	v_mfma_f32_16x16x32_bf16 v[48:51], v[152:155], v[160:163], 0
	v_mfma_f32_16x16x32_bf16 v[36:39], v[144:147], v[170:173], 0
	v_mfma_f32_16x16x32_bf16 v[32:35], v[152:155], v[170:173], 0
	v_mfma_f32_16x16x32_bf16 v[20:23], v[144:147], v[202:205], 0
	v_mfma_f32_16x16x32_bf16 v[16:19], v[152:155], v[202:205], 0
	v_mfma_f32_16x16x32_bf16 v[4:7], v[144:147], v[210:213], 0
	v_mfma_f32_16x16x32_bf16 v[0:3], v[152:155], v[210:213], 0
	v_mfma_f32_16x16x32_bf16 v[52:55], v[148:151], v[164:167], v[52:55]
	v_mfma_f32_16x16x32_bf16 v[48:51], v[156:159], v[164:167], v[48:51]
	v_mfma_f32_16x16x32_bf16 v[36:39], v[148:151], v[198:201], v[36:39]
	v_mfma_f32_16x16x32_bf16 v[32:35], v[156:159], v[198:201], v[32:35]
	s_add_i32 s64, 0, 0x18000
	v_mfma_f32_16x16x32_bf16 v[20:23], v[148:151], v[206:209], v[20:23]
	s_add_i32 s65, 0, 0x1c000
	v_mfma_f32_16x16x32_bf16 v[16:19], v[156:159], v[206:209], v[16:19]
	v_add_u32_e32 v240, s64, v224
	v_mfma_f32_16x16x32_bf16 v[4:7], v[148:151], v[214:217], v[4:7]
	v_add_u32_e32 v241, s65, v224
	v_mfma_f32_16x16x32_bf16 v[0:3], v[156:159], v[214:217], v[0:3]
	s_setprio 0
	s_barrier
; #define PG8_STAGE(bufoff, gbase, voff) do { _Pragma("unroll") for (int _i = 0; _i < 2; ++_i) \
;         __builtin_amdgcn_global_load_lds((const unsigned*)((const char*)(gbase) + (voff)[_i]), (PG8_LAS unsigned*)(lds + (bufoff) + ldsw + _i * 8192), 16, 0, 0); } while (0)
; #define PG8_LDA(dst, b, h) do { _Pragma("unroll") for (int m = 0; m < 4; ++m) _Pragma("unroll") for (int k = 0; k < 2; ++k) dst[m][k] = *(const PG8_LAS bf16x8*)(lds + PG8_SA(b, h) + aoff + m * 2048 + k * 1024); } while (0)
; #define PG8_LDB(dst, b, h) do { _Pragma("unroll") for (int n = 0; n < 2; ++n) _Pragma("unroll") for (int k = 0; k < 2; ++k) dst[n][k] = *(const PG8_LAS bf16x8*)(lds + PG8_SB(b, h) + boff + n * 2048 + k * 1024); } while (0)
; #define PG8_MMA(ai, bj, At, Bt) do { __builtin_amdgcn_s_setprio(1); _Pragma("unroll") for (int m = 0; m < 4; ++m) _Pragma("unroll") for (int n = 0; n < 2; ++n) _Pragma("unroll") for (int k = 0; k < 2; ++k) \
;         acc[ai][bj][m][n] = __builtin_amdgcn_mfma_f32_16x16x32_bf16(Bt[n][k], At[m][k], acc[ai][bj][m][n], 0, 0, 0); __builtin_amdgcn_s_setprio(0); } while (0)
; #define PG8_WAIT_V(n) asm volatile("s_waitcnt vmcnt(" #n ")" ::: "memory")
; #define PG8_WAIT_L(n) asm volatile("s_waitcnt lgkmcnt(" #n ")" ::: "memory")
; #define PG8_BAR __builtin_amdgcn_s_barrier()
; #define PG8_SCHED __builtin_amdgcn_sched_barrier(0)
; template <class Epi, class Sched, bool ALIGN_EPI = false, bool SP2 = false>
; __device__ __forceinline__ void gemm_phase(PG8_LAS unsigned char* lds, const Gemm g, const Sched& S, const Epi& E) {
;     ...
;             PG8_LDB(B0, 1, 0); PG8_LDB(B1, 1, 1); PG8_SCHED; PG8_LDA(At, 1, 0); PG8_STAGE(PG8_SA(0, 1), a2 + hstepA, voffA);
;             PG8_WAIT_V(8); PG8_WAIT_L(0); PG8_BAR; PG8_MMA(0, 0, At, B0); PG8_MMA(0, 1, At, B1); PG8_BAR; PG8_SCHED;
	ds_read_b128 v[128:131], v240
	ds_read_b128 v[132:135], v240 offset:1024
	ds_read_b128 v[136:139], v240 offset:2048
	ds_read_b128 v[140:143], v240 offset:3072
	ds_read_b128 v[144:147], v241
	ds_read_b128 v[148:151], v241 offset:1024
	ds_read_b128 v[152:155], v241 offset:2048
	ds_read_b128 v[156:159], v241 offset:3072
	ds_read_b128 v[160:163], v225 offset:32768
	ds_read_b128 v[164:167], v225 offset:33792
	ds_read_b128 v[170:173], v225 offset:34816
	ds_read_b128 v[198:201], v225 offset:35840
	ds_read_b128 v[202:205], v225 offset:36864
	ds_read_b128 v[206:209], v225 offset:37888
	ds_read_b128 v[210:213], v225 offset:38912
	ds_read_b128 v[214:217], v225 offset:39936
	s_add_u32 s56, s56, 0xb0000
	s_addc_u32 s57, s57, 0
	s_mov_b32 m0, s35
	v_lshl_add_u64 v[220:221], s[56:57], 0, v[192:193]
	global_load_lds_dwordx4 v[220:221], off
	v_lshl_add_u64 v[220:221], s[56:57], 0, v[190:191]
	s_mov_b32 m0, s60
	s_nop 0
	global_load_lds_dwordx4 v[220:221], off
	s_waitcnt vmcnt(8)
	s_waitcnt lgkmcnt(0)
	s_barrier
	s_setprio 1
	v_mfma_f32_16x16x32_bf16 v[124:127], v[128:131], v[160:163], v[124:127]
	v_mfma_f32_16x16x32_bf16 v[120:123], v[136:139], v[160:163], v[120:123]
	v_mfma_f32_16x16x32_bf16 v[108:111], v[128:131], v[170:173], v[108:111]
	v_mfma_f32_16x16x32_bf16 v[104:107], v[136:139], v[170:173], v[104:107]
	v_mfma_f32_16x16x32_bf16 v[92:95], v[128:131], v[202:205], v[92:95]
	v_mfma_f32_16x16x32_bf16 v[88:91], v[136:139], v[202:205], v[88:91]
	v_mfma_f32_16x16x32_bf16 v[76:79], v[128:131], v[210:213], v[76:79]
	v_mfma_f32_16x16x32_bf16 v[72:75], v[136:139], v[210:213], v[72:75]
	v_mfma_f32_16x16x32_bf16 v[124:127], v[132:135], v[164:167], v[124:127]
	v_mfma_f32_16x16x32_bf16 v[120:123], v[140:143], v[164:167], v[120:123]
	v_mfma_f32_16x16x32_bf16 v[108:111], v[132:135], v[198:201], v[108:111]
	v_mfma_f32_16x16x32_bf16 v[104:107], v[140:143], v[198:201], v[104:107]
	v_mfma_f32_16x16x32_bf16 v[92:95], v[132:135], v[206:209], v[92:95]
	v_mfma_f32_16x16x32_bf16 v[88:91], v[140:143], v[206:209], v[88:91]
	v_mfma_f32_16x16x32_bf16 v[76:79], v[132:135], v[214:217], v[76:79]
	v_mfma_f32_16x16x32_bf16 v[72:75], v[140:143], v[214:217], v[72:75]
	s_setprio 0
	s_setprio 1
	v_mfma_f32_16x16x32_bf16 v[116:119], v[144:147], v[160:163], v[116:119]
	v_mfma_f32_16x16x32_bf16 v[112:115], v[152:155], v[160:163], v[112:115]
	v_mfma_f32_16x16x32_bf16 v[100:103], v[144:147], v[170:173], v[100:103]
	v_mfma_f32_16x16x32_bf16 v[96:99], v[152:155], v[170:173], v[96:99]
	v_mfma_f32_16x16x32_bf16 v[84:87], v[144:147], v[202:205], v[84:87]
	v_mfma_f32_16x16x32_bf16 v[80:83], v[152:155], v[202:205], v[80:83]
	v_mfma_f32_16x16x32_bf16 v[68:71], v[144:147], v[210:213], v[68:71]
	v_mfma_f32_16x16x32_bf16 v[64:67], v[152:155], v[210:213], v[64:67]
	v_mfma_f32_16x16x32_bf16 v[116:119], v[148:151], v[164:167], v[116:119]
	v_mfma_f32_16x16x32_bf16 v[112:115], v[156:159], v[164:167], v[112:115]
	v_mfma_f32_16x16x32_bf16 v[100:103], v[148:151], v[198:201], v[100:103]
	v_mfma_f32_16x16x32_bf16 v[96:99], v[156:159], v[198:201], v[96:99]
	v_mfma_f32_16x16x32_bf16 v[84:87], v[148:151], v[206:209], v[84:87]
	s_add_i32 s56, s64, s2
	v_mfma_f32_16x16x32_bf16 v[80:83], v[156:159], v[206:209], v[80:83]
	v_lshl_add_u64 v[178:179], v[178:179], 0, s[30:31]
	v_mfma_f32_16x16x32_bf16 v[68:71], v[148:151], v[214:217], v[68:71]
	s_mov_b32 m0, s56
	v_mfma_f32_16x16x32_bf16 v[64:67], v[156:159], v[214:217], v[64:67]
	s_setprio 0
	s_barrier
; #define PG8_STAGE(bufoff, gbase, voff) do { _Pragma("unroll") for (int _i = 0; _i < 2; ++_i) \
;         __builtin_amdgcn_global_load_lds((const unsigned*)((const char*)(gbase) + (voff)[_i]), (PG8_LAS unsigned*)(lds + (bufoff) + ldsw + _i * 8192), 16, 0, 0); } while (0)
; #define PG8_LDA(dst, b, h) do { _Pragma("unroll") for (int m = 0; m < 4; ++m) _Pragma("unroll") for (int k = 0; k < 2; ++k) dst[m][k] = *(const PG8_LAS bf16x8*)(lds + PG8_SA(b, h) + aoff + m * 2048 + k * 1024); } while (0)
; #define PG8_LDB(dst, b, h) do { _Pragma("unroll") for (int n = 0; n < 2; ++n) _Pragma("unroll") for (int k = 0; k < 2; ++k) dst[n][k] = *(const PG8_LAS bf16x8*)(lds + PG8_SB(b, h) + boff + n * 2048 + k * 1024); } while (0)
; template <class Epi, class Sched, bool ALIGN_EPI = false, bool SP2 = false>
; __device__ __forceinline__ void gemm_phase(PG8_LAS unsigned char* lds, const Gemm g, const Sched& S, const Epi& E) {
;     ...
;         for (int t = 0; t < nt; t += 2) {
;             const bool last = (t == nt - 2);
;             const char* a1 = cA + (size_t)(t + 1) * kstepA;
;             const char* a2 = last ? nA : cA + (size_t)(t + 2) * kstepA; const char* b2 = last ? nB : cB + (size_t)(t + 2) * kstep;
;             const char* a3 = a2 + kstepA; const char* b3 = b2 + kstep;
;             if (last && has_next) S.a_ready(nxt);
;             if constexpr (SP2) {
;             PG8_LDB(B0, 0, 0); PG8_LDB(B1, 0, 1); PG8_SCHED; PG8_LDA(At, 0, 0); PG8_STAGE(PG8_SA(1, 1), a1 + hstepA, voffA);
;             PG8_WAIT_V(8); PG8_WAIT_L(0); PG8_BAR; PG8_MMA(0, 0, At, B0); PG8_MMA(0, 1, At, B1); PG8_BAR; PG8_SCHED;
;             PG8_LDA(At, 0, 1); PG8_STAGE(PG8_SB(0, 0), b2, voffB); PG8_STAGE(PG8_SB(0, 1), b2 + hstep, voffB); PG8_STAGE(PG8_SA(0, 0), a2, voffA);
;             PG8_WAIT_V(8); PG8_WAIT_L(0); PG8_BAR; PG8_MMA(1, 0, At, B0); PG8_MMA(1, 1, At, B1); PG8_BAR; PG8_SCHED;
;             PG8_LDB(B0, 1, 0); PG8_LDB(B1, 1, 1); PG8_SCHED; PG8_LDA(At, 1, 0); PG8_STAGE(PG8_SA(0, 1), a2 + hstepA, voffA);
;             PG8_WAIT_V(8); PG8_WAIT_L(0); PG8_BAR; PG8_MMA(0, 0, At, B0); PG8_MMA(0, 1, At, B1); PG8_BAR; PG8_SCHED;
;             PG8_LDA(At, 1, 1); PG8_STAGE(PG8_SB(1, 0), b3, voffB); PG8_STAGE(PG8_SB(1, 1), b3 + hstep, voffB); PG8_STAGE(PG8_SA(1, 0), a3, voffA);
;             PG8_WAIT_V(8); PG8_WAIT_L(0); PG8_BAR; PG8_MMA(1, 0, At, B0); PG8_MMA(1, 1, At, B1); PG8_BAR; PG8_SCHED;
	ds_read_b128 v[160:163], v225 offset:49152
	ds_read_b128 v[164:167], v225 offset:50176
	ds_read_b128 v[170:173], v225 offset:51200
	ds_read_b128 v[198:201], v225 offset:52224
	ds_read_b128 v[202:205], v225 offset:53248
	ds_read_b128 v[206:209], v225 offset:54272
	ds_read_b128 v[210:213], v225 offset:55296
	ds_read_b128 v[214:217], v225 offset:56320
	global_load_lds_dwordx4 v[178:179], off
	s_add_i32 m0, s56, 0x2000
	s_add_u32 s54, s54, 0xb0080
	v_lshl_add_u64 v[178:179], v[218:219], 0, s[30:31]
	s_addc_u32 s55, s55, 0
	s_add_i32 s56, s65, s2
	global_load_lds_dwordx4 v[178:179], off
	v_lshl_add_u64 v[178:179], s[54:55], 0, v[168:169]
	s_mov_b32 m0, s56
	s_nop 0
	global_load_lds_dwordx4 v[178:179], off
	v_lshl_add_u64 v[178:179], s[54:55], 0, v[188:189]
	s_add_i32 m0, s56, 0x2000
	s_nop 0
	global_load_lds_dwordx4 v[178:179], off
	v_lshl_add_u64 v[178:179], s[52:53], 0, v[192:193]
	s_mov_b32 m0, s69
	s_nop 0
	global_load_lds_dwordx4 v[178:179], off
	v_lshl_add_u64 v[178:179], s[52:53], 0, v[190:191]
	s_mov_b32 m0, s73
	s_nop 0
	global_load_lds_dwordx4 v[178:179], off
	s_waitcnt vmcnt(8)
	s_waitcnt lgkmcnt(0)
	s_barrier
	s_setprio 1
	v_mfma_f32_16x16x32_bf16 v[60:63], v[128:131], v[160:163], v[60:63]
	v_mfma_f32_16x16x32_bf16 v[56:59], v[136:139], v[160:163], v[56:59]
	v_mfma_f32_16x16x32_bf16 v[44:47], v[128:131], v[170:173], v[44:47]
	v_mfma_f32_16x16x32_bf16 v[40:43], v[136:139], v[170:173], v[40:43]
	v_mfma_f32_16x16x32_bf16 v[28:31], v[128:131], v[202:205], v[28:31]
	v_mfma_f32_16x16x32_bf16 v[24:27], v[136:139], v[202:205], v[24:27]
	v_mfma_f32_16x16x32_bf16 v[12:15], v[128:131], v[210:213], v[12:15]
	v_mfma_f32_16x16x32_bf16 v[8:11], v[136:139], v[210:213], v[8:11]
	v_mfma_f32_16x16x32_bf16 v[60:63], v[132:135], v[164:167], v[60:63]
	v_mfma_f32_16x16x32_bf16 v[56:59], v[140:143], v[164:167], v[56:59]
	v_mfma_f32_16x16x32_bf16 v[44:47], v[132:135], v[198:201], v[44:47]
	v_mfma_f32_16x16x32_bf16 v[40:43], v[140:143], v[198:201], v[40:43]
	v_mfma_f32_16x16x32_bf16 v[28:31], v[132:135], v[206:209], v[28:31]
	v_mfma_f32_16x16x32_bf16 v[24:27], v[140:143], v[206:209], v[24:27]
	s_add_i32 s7, s7, 2
	v_mfma_f32_16x16x32_bf16 v[12:15], v[132:135], v[214:217], v[12:15]
	s_add_u32 s5, s5, 0x100
	v_mfma_f32_16x16x32_bf16 v[8:11], v[140:143], v[214:217], v[8:11]
	s_addc_u32 s6, s6, 0
	s_setprio 0
	s_setprio 1
	v_mfma_f32_16x16x32_bf16 v[52:55], v[144:147], v[160:163], v[52:55]
	s_add_u32 s40, s40, 0x8000
	v_mfma_f32_16x16x32_bf16 v[48:51], v[152:155], v[160:163], v[48:51]
	s_addc_u32 s41, s41, 0
	v_mfma_f32_16x16x32_bf16 v[36:39], v[144:147], v[170:173], v[36:39]
	s_add_u32 s52, s40, 0xfff54000
	v_mfma_f32_16x16x32_bf16 v[32:35], v[152:155], v[170:173], v[32:35]
	s_addc_u32 s53, s41, -1
	v_mfma_f32_16x16x32_bf16 v[20:23], v[144:147], v[202:205], v[20:23]
	s_cmp_eq_u32 s7, 40
	v_mfma_f32_16x16x32_bf16 v[16:19], v[152:155], v[202:205], v[16:19]
	s_cselect_b32 s56, s48, s52
	v_mfma_f32_16x16x32_bf16 v[4:7], v[144:147], v[210:213], v[4:7]
	s_cselect_b32 s57, s49, s53
	v_mfma_f32_16x16x32_bf16 v[0:3], v[152:155], v[210:213], v[0:3]
	s_cselect_b32 s54, s50, s5
	v_mfma_f32_16x16x32_bf16 v[52:55], v[148:151], v[164:167], v[52:55]
	s_cselect_b32 s55, s51, s6
	v_mfma_f32_16x16x32_bf16 v[48:51], v[156:159], v[164:167], v[48:51]
	s_add_u32 s52, s56, 0x4000
	v_mfma_f32_16x16x32_bf16 v[36:39], v[148:151], v[198:201], v[36:39]
	s_addc_u32 s53, s57, 0
	v_mfma_f32_16x16x32_bf16 v[32:35], v[156:159], v[198:201], v[32:35]
	s_add_i32 s64, 0, 0x10000
	v_mfma_f32_16x16x32_bf16 v[20:23], v[148:151], v[206:209], v[20:23]
	s_add_i32 s74, 0, 0x14000
	v_mfma_f32_16x16x32_bf16 v[16:19], v[156:159], v[206:209], v[16:19]
	v_add_u32_e32 v242, s64, v224
	v_mfma_f32_16x16x32_bf16 v[4:7], v[148:151], v[214:217], v[4:7]
	v_add_u32_e32 v243, s74, v224
	v_mfma_f32_16x16x32_bf16 v[0:3], v[156:159], v[214:217], v[0:3]
	s_setprio 0
	s_barrier
	.p2align	6

; #define PG8_STAGE(bufoff, gbase, voff) do { _Pragma("unroll") for (int _i = 0; _i < 2; ++_i) \
;         __builtin_amdgcn_global_load_lds((const unsigned*)((const char*)(gbase) + (voff)[_i]), (PG8_LAS unsigned*)(lds + (bufoff) + ldsw + _i * 8192), 16, 0, 0); } while (0)
; #define PG8_LDA(dst, b, h) do { _Pragma("unroll") for (int m = 0; m < 4; ++m) _Pragma("unroll") for (int k = 0; k < 2; ++k) dst[m][k] = *(const PG8_LAS bf16x8*)(lds + PG8_SA(b, h) + aoff + m * 2048 + k * 1024); } while (0)
; #define PG8_BAR __builtin_amdgcn_s_barrier()
; template <class Epi, class Sched, bool ALIGN_EPI = false, bool SP2 = false>
; __device__ __forceinline__ void gemm_phase(PG8_LAS unsigned char* lds, const Gemm g, const Sched& S, const Epi& E) {
;     ...
;         const char* nA = has_next ? (const char*)g.A + (size_t)nxt.pm * tstepA : cA; const char* nB = has_next ? (const char*)g.Bt + (size_t)nxt.pn * tstep : cB;
;         for (int t = 0; t < nt; t += 2) {
;             const bool last = (t == nt - 2);
;             const char* a1 = cA + (size_t)(t + 1) * kstepA;
;             const char* a2 = last ? nA : cA + (size_t)(t + 2) * kstepA; const char* b2 = last ? nB : cB + (size_t)(t + 2) * kstep;
;             const char* a3 = a2 + kstepA; const char* b3 = b2 + kstep;
;             if (last && has_next) S.a_ready(nxt);
;             if constexpr (SP2) {
;             PG8_LDB(B0, 0, 0); PG8_LDB(B1, 0, 1); PG8_SCHED; PG8_LDA(At, 0, 0); PG8_STAGE(PG8_SA(1, 1), a1 + hstepA, voffA);
;             PG8_WAIT_V(8); PG8_WAIT_L(0); PG8_BAR; PG8_MMA(0, 0, At, B0); PG8_MMA(0, 1, At, B1); PG8_BAR; PG8_SCHED;
;             PG8_LDA(At, 0, 1); PG8_STAGE(PG8_SB(0, 0), b2, voffB); PG8_STAGE(PG8_SB(0, 1), b2 + hstep, voffB); PG8_STAGE(PG8_SA(0, 0), a2, voffA);
;             PG8_WAIT_V(8); PG8_WAIT_L(0); PG8_BAR; PG8_MMA(1, 0, At, B0); PG8_MMA(1, 1, At, B1); PG8_BAR; PG8_SCHED;
;             PG8_LDB(B0, 1, 0); PG8_LDB(B1, 1, 1); PG8_SCHED; PG8_LDA(At, 1, 0); PG8_STAGE(PG8_SA(0, 1), a2 + hstepA, voffA);
;             PG8_WAIT_V(8); PG8_WAIT_L(0); PG8_BAR; PG8_MMA(0, 0, At, B0); PG8_MMA(0, 1, At, B1); PG8_BAR; PG8_SCHED;
;             PG8_LDA(At, 1, 1); PG8_STAGE(PG8_SB(1, 0), b3, voffB); PG8_STAGE(PG8_SB(1, 1), b3 + hstep, voffB); PG8_STAGE(PG8_SA(1, 0), a3, voffA);
;             PG8_WAIT_V(8); PG8_WAIT_L(0); PG8_BAR; PG8_MMA(1, 0, At, B0); PG8_MMA(1, 1, At, B1); PG8_BAR; PG8_SCHED;
.LBB0_973:
	s_add_u32 s5, s48, 0x100
	s_addc_u32 s6, s49, 0
	s_add_u32 s38, s50, 0xb4000
	s_addc_u32 s39, s51, 0
	s_mov_b32 s7, -2
	s_add_u32 s48, s38, 0xfff54000
	s_addc_u32 s49, s39, -1
	s_cmp_eq_u32 s7, 40
	s_cselect_b32 s52, s44, s48
	s_cselect_b32 s53, s45, s49
	s_cselect_b32 s50, s46, s5
	s_cselect_b32 s51, s47, s6
	s_add_u32 s48, s52, 0x4000
	s_addc_u32 s49, s53, 0
	s_add_i32 s64, 0, 0x10000
	s_add_i32 s74, 0, 0x14000
	s_add_i32 m0, s3, 0xc000
	v_lshl_add_u64 v[178:179], s[38:39], 0, v[196:197]
	global_load_lds_dwordx4 v[178:179], off
	v_lshl_add_u64 v[178:179], s[38:39], 0, v[194:195]
	s_add_i32 m0, s3, 0xe000
	s_nop 0
	global_load_lds_dwordx4 v[178:179], off
	s_waitcnt vmcnt(8)
	s_waitcnt lgkmcnt(0)
	s_barrier
	s_setprio 1
	v_mfma_f32_16x16x32_bf16 v[124:127], v[128:131], v[160:163], 0
	v_mfma_f32_16x16x32_bf16 v[120:123], v[136:139], v[160:163], 0
	v_mfma_f32_16x16x32_bf16 v[108:111], v[128:131], v[170:173], 0
	v_mfma_f32_16x16x32_bf16 v[104:107], v[136:139], v[170:173], 0
	v_mfma_f32_16x16x32_bf16 v[92:95], v[128:131], v[202:205], 0
	v_mfma_f32_16x16x32_bf16 v[88:91], v[136:139], v[202:205], 0
	v_mfma_f32_16x16x32_bf16 v[76:79], v[128:131], v[210:213], 0
	v_mfma_f32_16x16x32_bf16 v[72:75], v[136:139], v[210:213], 0
	v_mfma_f32_16x16x32_bf16 v[124:127], v[132:135], v[164:167], v[124:127]
	v_mfma_f32_16x16x32_bf16 v[120:123], v[140:143], v[164:167], v[120:123]
	v_mfma_f32_16x16x32_bf16 v[108:111], v[132:135], v[198:201], v[108:111]
	v_mfma_f32_16x16x32_bf16 v[104:107], v[140:143], v[198:201], v[104:107]
	v_mfma_f32_16x16x32_bf16 v[92:95], v[132:135], v[206:209], v[92:95]
	v_mfma_f32_16x16x32_bf16 v[88:91], v[140:143], v[206:209], v[88:91]
	v_mfma_f32_16x16x32_bf16 v[76:79], v[132:135], v[214:217], v[76:79]
	v_mfma_f32_16x16x32_bf16 v[72:75], v[140:143], v[214:217], v[72:75]
	s_setprio 0
	s_setprio 1
	v_mfma_f32_16x16x32_bf16 v[116:119], v[144:147], v[160:163], 0
	v_mfma_f32_16x16x32_bf16 v[112:115], v[152:155], v[160:163], 0
	v_mfma_f32_16x16x32_bf16 v[100:103], v[144:147], v[170:173], 0
	v_mfma_f32_16x16x32_bf16 v[96:99], v[152:155], v[170:173], 0
	v_mfma_f32_16x16x32_bf16 v[84:87], v[144:147], v[202:205], 0
	v_mfma_f32_16x16x32_bf16 v[80:83], v[152:155], v[202:205], 0
	v_mfma_f32_16x16x32_bf16 v[68:71], v[144:147], v[210:213], 0
	v_mfma_f32_16x16x32_bf16 v[64:67], v[152:155], v[210:213], 0
	v_mfma_f32_16x16x32_bf16 v[116:119], v[148:151], v[164:167], v[116:119]
	v_mfma_f32_16x16x32_bf16 v[112:115], v[156:159], v[164:167], v[112:115]
	v_mfma_f32_16x16x32_bf16 v[100:103], v[148:151], v[198:201], v[100:103]
	v_mfma_f32_16x16x32_bf16 v[96:99], v[156:159], v[198:201], v[96:99]
	v_mfma_f32_16x16x32_bf16 v[84:87], v[148:151], v[206:209], v[84:87]
	s_add_i32 s64, s64, s2
	v_mfma_f32_16x16x32_bf16 v[80:83], v[156:159], v[206:209], v[80:83]
	v_lshl_add_u64 v[178:179], s[50:51], 0, v[168:169]
	v_mfma_f32_16x16x32_bf16 v[68:71], v[148:151], v[214:217], v[68:71]
	s_mov_b32 m0, s64
	v_mfma_f32_16x16x32_bf16 v[64:67], v[156:159], v[214:217], v[64:67]
	s_setprio 0
	s_barrier
	ds_read_b128 v[160:163], v237 offset:16384
	ds_read_b128 v[164:167], v237 offset:17408
	ds_read_b128 v[170:173], v237 offset:18432
	ds_read_b128 v[198:201], v237 offset:19456
	ds_read_b128 v[202:205], v237 offset:20480
	ds_read_b128 v[206:209], v237 offset:21504
	ds_read_b128 v[210:213], v237 offset:22528
	ds_read_b128 v[214:217], v237 offset:23552
	global_load_lds_dwordx4 v[178:179], off
	s_add_i32 m0, s64, 0x2000
	s_add_u32 s64, s50, 0xb0000
	v_lshl_add_u64 v[218:219], s[50:51], 0, v[188:189]
	s_addc_u32 s65, s51, 0
	s_add_i32 s74, s74, s2
	global_load_lds_dwordx4 v[218:219], off
	v_lshl_add_u64 v[220:221], s[64:65], 0, v[168:169]
	s_mov_b32 m0, s74
	s_nop 0
	global_load_lds_dwordx4 v[220:221], off
	v_lshl_add_u64 v[220:221], s[64:65], 0, v[188:189]
	s_add_i32 m0, s74, 0x2000
	s_nop 0
	global_load_lds_dwordx4 v[220:221], off
	v_lshl_add_u64 v[220:221], s[52:53], 0, v[192:193]
	s_mov_b32 m0, s3
	s_nop 0
	global_load_lds_dwordx4 v[220:221], off
	v_lshl_add_u64 v[220:221], s[52:53], 0, v[190:191]
	s_mov_b32 m0, s34
	s_nop 0
	global_load_lds_dwordx4 v[220:221], off
	s_waitcnt vmcnt(8)
	s_waitcnt lgkmcnt(0)
	s_barrier
	s_setprio 1
	v_mfma_f32_16x16x32_bf16 v[60:63], v[128:131], v[160:163], 0
	v_mfma_f32_16x16x32_bf16 v[56:59], v[136:139], v[160:163], 0
	v_mfma_f32_16x16x32_bf16 v[44:47], v[128:131], v[170:173], 0
	v_mfma_f32_16x16x32_bf16 v[40:43], v[136:139], v[170:173], 0
	v_mfma_f32_16x16x32_bf16 v[28:31], v[128:131], v[202:205], 0
	v_mfma_f32_16x16x32_bf16 v[24:27], v[136:139], v[202:205], 0
	v_mfma_f32_16x16x32_bf16 v[12:15], v[128:131], v[210:213], 0
	v_mfma_f32_16x16x32_bf16 v[8:11], v[136:139], v[210:213], 0
	v_mfma_f32_16x16x32_bf16 v[60:63], v[132:135], v[164:167], v[60:63]
	v_mfma_f32_16x16x32_bf16 v[56:59], v[140:143], v[164:167], v[56:59]
	v_mfma_f32_16x16x32_bf16 v[44:47], v[132:135], v[198:201], v[44:47]
	v_mfma_f32_16x16x32_bf16 v[40:43], v[140:143], v[198:201], v[40:43]
	v_mfma_f32_16x16x32_bf16 v[28:31], v[132:135], v[206:209], v[28:31]
	v_mfma_f32_16x16x32_bf16 v[24:27], v[140:143], v[206:209], v[24:27]
	v_mfma_f32_16x16x32_bf16 v[12:15], v[132:135], v[214:217], v[12:15]
	v_mfma_f32_16x16x32_bf16 v[8:11], v[140:143], v[214:217], v[8:11]
	s_setprio 0
	s_setprio 1
	v_mfma_f32_16x16x32_bf16 v[52:55], v[144:147], v[160:163], 0
	v_mfma_f32_16x16x32_bf16 v[48:51], v[152:155], v[160:163], 0
	v_mfma_f32_16x16x32_bf16 v[36:39], v[144:147], v[170:173], 0
	v_mfma_f32_16x16x32_bf16 v[32:35], v[152:155], v[170:173], 0
	v_mfma_f32_16x16x32_bf16 v[20:23], v[144:147], v[202:205], 0
	v_mfma_f32_16x16x32_bf16 v[16:19], v[152:155], v[202:205], 0
	v_mfma_f32_16x16x32_bf16 v[4:7], v[144:147], v[210:213], 0
	v_mfma_f32_16x16x32_bf16 v[0:3], v[152:155], v[210:213], 0
	v_mfma_f32_16x16x32_bf16 v[52:55], v[148:151], v[164:167], v[52:55]
	v_mfma_f32_16x16x32_bf16 v[48:51], v[156:159], v[164:167], v[48:51]
	v_mfma_f32_16x16x32_bf16 v[36:39], v[148:151], v[198:201], v[36:39]
	v_mfma_f32_16x16x32_bf16 v[32:35], v[156:159], v[198:201], v[32:35]
	s_add_i32 s64, 0, 0x18000
	v_mfma_f32_16x16x32_bf16 v[20:23], v[148:151], v[206:209], v[20:23]
	s_add_i32 s65, 0, 0x1c000
	v_mfma_f32_16x16x32_bf16 v[16:19], v[156:159], v[206:209], v[16:19]
	v_add_u32_e32 v240, s64, v236
	v_mfma_f32_16x16x32_bf16 v[4:7], v[148:151], v[214:217], v[4:7]
	v_add_u32_e32 v241, s65, v236
	v_mfma_f32_16x16x32_bf16 v[0:3], v[156:159], v[214:217], v[0:3]
	s_setprio 0
	s_barrier
; #define PG8_STAGE(bufoff, gbase, voff) do { _Pragma("unroll") for (int _i = 0; _i < 2; ++_i) \
;         __builtin_amdgcn_global_load_lds((const unsigned*)((const char*)(gbase) + (voff)[_i]), (PG8_LAS unsigned*)(lds + (bufoff) + ldsw + _i * 8192), 16, 0, 0); } while (0)
; #define PG8_LDA(dst, b, h) do { _Pragma("unroll") for (int m = 0; m < 4; ++m) _Pragma("unroll") for (int k = 0; k < 2; ++k) dst[m][k] = *(const PG8_LAS bf16x8*)(lds + PG8_SA(b, h) + aoff + m * 2048 + k * 1024); } while (0)
; #define PG8_LDB(dst, b, h) do { _Pragma("unroll") for (int n = 0; n < 2; ++n) _Pragma("unroll") for (int k = 0; k < 2; ++k) dst[n][k] = *(const PG8_LAS bf16x8*)(lds + PG8_SB(b, h) + boff + n * 2048 + k * 1024); } while (0)
; #define PG8_MMA(ai, bj, At, Bt) do { __builtin_amdgcn_s_setprio(1); _Pragma("unroll") for (int m = 0; m < 4; ++m) _Pragma("unroll") for (int n = 0; n < 2; ++n) _Pragma("unroll") for (int k = 0; k < 2; ++k) \
;         acc[ai][bj][m][n] = __builtin_amdgcn_mfma_f32_16x16x32_bf16(Bt[n][k], At[m][k], acc[ai][bj][m][n], 0, 0, 0); __builtin_amdgcn_s_setprio(0); } while (0)
; #define PG8_WAIT_V(n) asm volatile("s_waitcnt vmcnt(" #n ")" ::: "memory")
; #define PG8_WAIT_L(n) asm volatile("s_waitcnt lgkmcnt(" #n ")" ::: "memory")
; #define PG8_BAR __builtin_amdgcn_s_barrier()
; #define PG8_SCHED __builtin_amdgcn_sched_barrier(0)
; template <class Epi, class Sched, bool ALIGN_EPI = false, bool SP2 = false>
; __device__ __forceinline__ void gemm_phase(PG8_LAS unsigned char* lds, const Gemm g, const Sched& S, const Epi& E) {
;     ...
;             PG8_LDB(B0, 1, 0); PG8_LDB(B1, 1, 1); PG8_SCHED; PG8_LDA(At, 1, 0); PG8_STAGE(PG8_SA(0, 1), a2 + hstepA, voffA);
;             PG8_WAIT_V(8); PG8_WAIT_L(0); PG8_BAR; PG8_MMA(0, 0, At, B0); PG8_MMA(0, 1, At, B1); PG8_BAR; PG8_SCHED;
	ds_read_b128 v[128:131], v240
	ds_read_b128 v[132:135], v240 offset:1024
	ds_read_b128 v[136:139], v240 offset:2048
	ds_read_b128 v[140:143], v240 offset:3072
	ds_read_b128 v[144:147], v241
	ds_read_b128 v[148:151], v241 offset:1024
	ds_read_b128 v[152:155], v241 offset:2048
	ds_read_b128 v[156:159], v241 offset:3072
	ds_read_b128 v[160:163], v237 offset:32768
	ds_read_b128 v[164:167], v237 offset:33792
	ds_read_b128 v[170:173], v237 offset:34816
	ds_read_b128 v[198:201], v237 offset:35840
	ds_read_b128 v[202:205], v237 offset:36864
	ds_read_b128 v[206:209], v237 offset:37888
	ds_read_b128 v[210:213], v237 offset:38912
	ds_read_b128 v[214:217], v237 offset:39936
	s_add_u32 s52, s52, 0xb0000
	s_addc_u32 s53, s53, 0
	s_mov_b32 m0, s35
	v_lshl_add_u64 v[220:221], s[52:53], 0, v[192:193]
	global_load_lds_dwordx4 v[220:221], off
	v_lshl_add_u64 v[220:221], s[52:53], 0, v[190:191]
	s_mov_b32 m0, s54
	s_nop 0
	global_load_lds_dwordx4 v[220:221], off
	s_waitcnt vmcnt(8)
	s_waitcnt lgkmcnt(0)
	s_barrier
	s_setprio 1
	v_mfma_f32_16x16x32_bf16 v[124:127], v[128:131], v[160:163], v[124:127]
	v_mfma_f32_16x16x32_bf16 v[120:123], v[136:139], v[160:163], v[120:123]
	v_mfma_f32_16x16x32_bf16 v[108:111], v[128:131], v[170:173], v[108:111]
	v_mfma_f32_16x16x32_bf16 v[104:107], v[136:139], v[170:173], v[104:107]
	v_mfma_f32_16x16x32_bf16 v[92:95], v[128:131], v[202:205], v[92:95]
	v_mfma_f32_16x16x32_bf16 v[88:91], v[136:139], v[202:205], v[88:91]
	v_mfma_f32_16x16x32_bf16 v[76:79], v[128:131], v[210:213], v[76:79]
	v_mfma_f32_16x16x32_bf16 v[72:75], v[136:139], v[210:213], v[72:75]
	v_mfma_f32_16x16x32_bf16 v[124:127], v[132:135], v[164:167], v[124:127]
	v_mfma_f32_16x16x32_bf16 v[120:123], v[140:143], v[164:167], v[120:123]
	v_mfma_f32_16x16x32_bf16 v[108:111], v[132:135], v[198:201], v[108:111]
	v_mfma_f32_16x16x32_bf16 v[104:107], v[140:143], v[198:201], v[104:107]
	v_mfma_f32_16x16x32_bf16 v[92:95], v[132:135], v[206:209], v[92:95]
	v_mfma_f32_16x16x32_bf16 v[88:91], v[140:143], v[206:209], v[88:91]
	v_mfma_f32_16x16x32_bf16 v[76:79], v[132:135], v[214:217], v[76:79]
	v_mfma_f32_16x16x32_bf16 v[72:75], v[140:143], v[214:217], v[72:75]
	s_setprio 0
	s_setprio 1
	v_mfma_f32_16x16x32_bf16 v[116:119], v[144:147], v[160:163], v[116:119]
	v_mfma_f32_16x16x32_bf16 v[112:115], v[152:155], v[160:163], v[112:115]
	v_mfma_f32_16x16x32_bf16 v[100:103], v[144:147], v[170:173], v[100:103]
	v_mfma_f32_16x16x32_bf16 v[96:99], v[152:155], v[170:173], v[96:99]
	v_mfma_f32_16x16x32_bf16 v[84:87], v[144:147], v[202:205], v[84:87]
	v_mfma_f32_16x16x32_bf16 v[80:83], v[152:155], v[202:205], v[80:83]
	v_mfma_f32_16x16x32_bf16 v[68:71], v[144:147], v[210:213], v[68:71]
	v_mfma_f32_16x16x32_bf16 v[64:67], v[152:155], v[210:213], v[64:67]
	v_mfma_f32_16x16x32_bf16 v[116:119], v[148:151], v[164:167], v[116:119]
	v_mfma_f32_16x16x32_bf16 v[112:115], v[156:159], v[164:167], v[112:115]
	v_mfma_f32_16x16x32_bf16 v[100:103], v[148:151], v[198:201], v[100:103]
	v_mfma_f32_16x16x32_bf16 v[96:99], v[156:159], v[198:201], v[96:99]
	v_mfma_f32_16x16x32_bf16 v[84:87], v[148:151], v[206:209], v[84:87]
	s_add_i32 s52, s64, s2
	v_mfma_f32_16x16x32_bf16 v[80:83], v[156:159], v[206:209], v[80:83]
	v_lshl_add_u64 v[178:179], v[178:179], 0, s[30:31]
	v_mfma_f32_16x16x32_bf16 v[68:71], v[148:151], v[214:217], v[68:71]
	s_mov_b32 m0, s52
	v_mfma_f32_16x16x32_bf16 v[64:67], v[156:159], v[214:217], v[64:67]
	s_setprio 0
	s_barrier
; #define PG8_STAGE(bufoff, gbase, voff) do { _Pragma("unroll") for (int _i = 0; _i < 2; ++_i) \
;         __builtin_amdgcn_global_load_lds((const unsigned*)((const char*)(gbase) + (voff)[_i]), (PG8_LAS unsigned*)(lds + (bufoff) + ldsw + _i * 8192), 16, 0, 0); } while (0)
; #define PG8_LDA(dst, b, h) do { _Pragma("unroll") for (int m = 0; m < 4; ++m) _Pragma("unroll") for (int k = 0; k < 2; ++k) dst[m][k] = *(const PG8_LAS bf16x8*)(lds + PG8_SA(b, h) + aoff + m * 2048 + k * 1024); } while (0)
; #define PG8_LDB(dst, b, h) do { _Pragma("unroll") for (int n = 0; n < 2; ++n) _Pragma("unroll") for (int k = 0; k < 2; ++k) dst[n][k] = *(const PG8_LAS bf16x8*)(lds + PG8_SB(b, h) + boff + n * 2048 + k * 1024); } while (0)
; template <class Epi, class Sched, bool ALIGN_EPI = false, bool SP2 = false>
; __device__ __forceinline__ void gemm_phase(PG8_LAS unsigned char* lds, const Gemm g, const Sched& S, const Epi& E) {
;     ...
;         for (int t = 0; t < nt; t += 2) {
;             const bool last = (t == nt - 2);
;             const char* a1 = cA + (size_t)(t + 1) * kstepA;
;             const char* a2 = last ? nA : cA + (size_t)(t + 2) * kstepA; const char* b2 = last ? nB : cB + (size_t)(t + 2) * kstep;
;             const char* a3 = a2 + kstepA; const char* b3 = b2 + kstep;
;             if (last && has_next) S.a_ready(nxt);
;             if constexpr (SP2) {
;             PG8_LDB(B0, 0, 0); PG8_LDB(B1, 0, 1); PG8_SCHED; PG8_LDA(At, 0, 0); PG8_STAGE(PG8_SA(1, 1), a1 + hstepA, voffA);
;             PG8_WAIT_V(8); PG8_WAIT_L(0); PG8_BAR; PG8_MMA(0, 0, At, B0); PG8_MMA(0, 1, At, B1); PG8_BAR; PG8_SCHED;
;             PG8_LDA(At, 0, 1); PG8_STAGE(PG8_SB(0, 0), b2, voffB); PG8_STAGE(PG8_SB(0, 1), b2 + hstep, voffB); PG8_STAGE(PG8_SA(0, 0), a2, voffA);
;             PG8_WAIT_V(8); PG8_WAIT_L(0); PG8_BAR; PG8_MMA(1, 0, At, B0); PG8_MMA(1, 1, At, B1); PG8_BAR; PG8_SCHED;
;             PG8_LDB(B0, 1, 0); PG8_LDB(B1, 1, 1); PG8_SCHED; PG8_LDA(At, 1, 0); PG8_STAGE(PG8_SA(0, 1), a2 + hstepA, voffA);
;             PG8_WAIT_V(8); PG8_WAIT_L(0); PG8_BAR; PG8_MMA(0, 0, At, B0); PG8_MMA(0, 1, At, B1); PG8_BAR; PG8_SCHED;
;             PG8_LDA(At, 1, 1); PG8_STAGE(PG8_SB(1, 0), b3, voffB); PG8_STAGE(PG8_SB(1, 1), b3 + hstep, voffB); PG8_STAGE(PG8_SA(1, 0), a3, voffA);
;             PG8_WAIT_V(8); PG8_WAIT_L(0); PG8_BAR; PG8_MMA(1, 0, At, B0); PG8_MMA(1, 1, At, B1); PG8_BAR; PG8_SCHED;
	ds_read_b128 v[160:163], v237 offset:49152
	ds_read_b128 v[164:167], v237 offset:50176
	ds_read_b128 v[170:173], v237 offset:51200
	ds_read_b128 v[198:201], v237 offset:52224
	ds_read_b128 v[202:205], v237 offset:53248
	ds_read_b128 v[206:209], v237 offset:54272
	ds_read_b128 v[210:213], v237 offset:55296
	ds_read_b128 v[214:217], v237 offset:56320
	global_load_lds_dwordx4 v[178:179], off
	s_add_i32 m0, s52, 0x2000
	s_add_u32 s50, s50, 0xb0080
	v_lshl_add_u64 v[178:179], v[218:219], 0, s[30:31]
	s_addc_u32 s51, s51, 0
	s_add_i32 s52, s65, s2
	global_load_lds_dwordx4 v[178:179], off
	v_lshl_add_u64 v[178:179], s[50:51], 0, v[168:169]
	s_mov_b32 m0, s52
	s_nop 0
	global_load_lds_dwordx4 v[178:179], off
	v_lshl_add_u64 v[178:179], s[50:51], 0, v[188:189]
	s_add_i32 m0, s52, 0x2000
	s_nop 0
	global_load_lds_dwordx4 v[178:179], off
	v_lshl_add_u64 v[178:179], s[48:49], 0, v[192:193]
	s_mov_b32 m0, s57
	s_nop 0
	global_load_lds_dwordx4 v[178:179], off
	v_lshl_add_u64 v[178:179], s[48:49], 0, v[190:191]
	s_mov_b32 m0, s60
	s_nop 0
	global_load_lds_dwordx4 v[178:179], off
	s_waitcnt vmcnt(8)
	s_waitcnt lgkmcnt(0)
	s_barrier
	s_setprio 1
	v_mfma_f32_16x16x32_bf16 v[60:63], v[128:131], v[160:163], v[60:63]
	v_mfma_f32_16x16x32_bf16 v[56:59], v[136:139], v[160:163], v[56:59]
	v_mfma_f32_16x16x32_bf16 v[44:47], v[128:131], v[170:173], v[44:47]
	v_mfma_f32_16x16x32_bf16 v[40:43], v[136:139], v[170:173], v[40:43]
	v_mfma_f32_16x16x32_bf16 v[28:31], v[128:131], v[202:205], v[28:31]
	v_mfma_f32_16x16x32_bf16 v[24:27], v[136:139], v[202:205], v[24:27]
	v_mfma_f32_16x16x32_bf16 v[12:15], v[128:131], v[210:213], v[12:15]
	v_mfma_f32_16x16x32_bf16 v[8:11], v[136:139], v[210:213], v[8:11]
	v_mfma_f32_16x16x32_bf16 v[60:63], v[132:135], v[164:167], v[60:63]
	v_mfma_f32_16x16x32_bf16 v[56:59], v[140:143], v[164:167], v[56:59]
	v_mfma_f32_16x16x32_bf16 v[44:47], v[132:135], v[198:201], v[44:47]
	v_mfma_f32_16x16x32_bf16 v[40:43], v[140:143], v[198:201], v[40:43]
	v_mfma_f32_16x16x32_bf16 v[28:31], v[132:135], v[206:209], v[28:31]
	v_mfma_f32_16x16x32_bf16 v[24:27], v[140:143], v[206:209], v[24:27]
	s_add_i32 s7, s7, 2
	v_mfma_f32_16x16x32_bf16 v[12:15], v[132:135], v[214:217], v[12:15]
	s_add_u32 s5, s5, 0x100
	v_mfma_f32_16x16x32_bf16 v[8:11], v[140:143], v[214:217], v[8:11]
	s_addc_u32 s6, s6, 0
	s_setprio 0
	s_setprio 1
	v_mfma_f32_16x16x32_bf16 v[52:55], v[144:147], v[160:163], v[52:55]
	s_add_u32 s38, s38, 0x8000
	v_mfma_f32_16x16x32_bf16 v[48:51], v[152:155], v[160:163], v[48:51]
	s_addc_u32 s39, s39, 0
	v_mfma_f32_16x16x32_bf16 v[36:39], v[144:147], v[170:173], v[36:39]
	s_add_u32 s48, s38, 0xfff54000
	v_mfma_f32_16x16x32_bf16 v[32:35], v[152:155], v[170:173], v[32:35]
	s_addc_u32 s49, s39, -1
	v_mfma_f32_16x16x32_bf16 v[20:23], v[144:147], v[202:205], v[20:23]
	s_cmp_eq_u32 s7, 40
	v_mfma_f32_16x16x32_bf16 v[16:19], v[152:155], v[202:205], v[16:19]
	s_cselect_b32 s52, s44, s48
	v_mfma_f32_16x16x32_bf16 v[4:7], v[144:147], v[210:213], v[4:7]
	s_cselect_b32 s53, s45, s49
	v_mfma_f32_16x16x32_bf16 v[0:3], v[152:155], v[210:213], v[0:3]
	s_cselect_b32 s50, s46, s5
	v_mfma_f32_16x16x32_bf16 v[52:55], v[148:151], v[164:167], v[52:55]
	s_cselect_b32 s51, s47, s6
	v_mfma_f32_16x16x32_bf16 v[48:51], v[156:159], v[164:167], v[48:51]
	s_add_u32 s48, s52, 0x4000
	v_mfma_f32_16x16x32_bf16 v[36:39], v[148:151], v[198:201], v[36:39]
	s_addc_u32 s49, s53, 0
	v_mfma_f32_16x16x32_bf16 v[32:35], v[156:159], v[198:201], v[32:35]
	s_add_i32 s64, 0, 0x10000
	v_mfma_f32_16x16x32_bf16 v[20:23], v[148:151], v[206:209], v[20:23]
	s_add_i32 s74, 0, 0x14000
	v_mfma_f32_16x16x32_bf16 v[16:19], v[156:159], v[206:209], v[16:19]
	v_add_u32_e32 v242, s64, v236
	v_mfma_f32_16x16x32_bf16 v[4:7], v[148:151], v[214:217], v[4:7]
	v_add_u32_e32 v243, s74, v236
	v_mfma_f32_16x16x32_bf16 v[0:3], v[156:159], v[214:217], v[0:3]
	s_setprio 0
	s_barrier
	.p2align	6
